# Resid epilogues: residual loads of all 8 row groups issued up front (12 hoisted into dead fragment registers) instead of one group ahead; on top of peel + saddr + combine + readback
# speedup vs baseline: 1.0038x; 1.0038x over previous
; __device__ __forceinline__ unsigned cvt_pk_bf16(float lo, float hi) { unsigned r; asm volatile("v_cvt_pk_bf16_f32 %0, %1, %2" : "=v"(r) : "v"(lo), "v"(hi)); return r; }
;     __device__ __forceinline__ void operator()(const f32x4 (&acc)[2][2][4][2], const Unit& u, int wr, int wc, int fr, int fq, const float (&)[8]) const {
;         const int row0 = u.pm * BM + wr * 64 + fr, col0 = u.pn * BM + wc * 32 + 8 * fq;
;         u32x4 xc[2], xn[2];
;         { const size_t off = (size_t)row0 * 2048 + col0;
; #pragma unroll
;           for (int bj = 0; bj < 2; ++bj) xc[bj] = *(const u32x4*)(xb + off + bj * HALF); }
; #pragma unroll
;         for (int g = 0; g < 8; ++g) { const int ai = g >> 2, m = g & 3, row = row0 + ai * HALF + m * 16; const size_t off = (size_t)row * 2048 + col0; float ss = 0.f;
;             if (g + 1 < 8) { const size_t offn = (size_t)(row0 + ((g + 1) >> 2) * HALF + ((g + 1) & 3) * 16) * 2048 + col0;
; #pragma unroll
;                 for (int bj = 0; bj < 2; ++bj) xn[bj] = *(const u32x4*)(xb + offn + bj * HALF); }
; #pragma unroll
;             for (int bj = 0; bj < 2; ++bj) { const size_t o = off + bj * HALF; const u32x4 xw = xc[bj];
;                 const f32x4 x0 = (f32x4){__uint_as_float(xw.x << 16), __uint_as_float(xw.x & 0xffff0000u), __uint_as_float(xw.y << 16), __uint_as_float(xw.y & 0xffff0000u)};
;                 const f32x4 x1 = (f32x4){__uint_as_float(xw.z << 16), __uint_as_float(xw.z & 0xffff0000u), __uint_as_float(xw.w << 16), __uint_as_float(xw.w & 0xffff0000u)};
;                 const f32x4 v0 = x0 + acc[ai][bj][m][0] * alpha, v1 = x1 + acc[ai][bj][m][1] * alpha;
;                 if (xf) { *(f32x4*)(xf + o) = v0; *(f32x4*)(xf + o + 4) = v1; }
;                 else { u32x4 w; w.x = cvt_pk_bf16(v0[0], v0[1]); w.y = cvt_pk_bf16(v0[2], v0[3]); w.z = cvt_pk_bf16(v1[0], v1[1]); w.w = cvt_pk_bf16(v1[2], v1[3]); *(u32x4*)(xb + o) = w; }
;                 ss += ((v0[0] * v0[0] + v0[1] * v0[1]) + (v0[2] * v0[2] + v0[3] * v0[3])) + ((v1[0] * v1[0] + v1[1] * v1[1]) + (v1[2] * v1[2] + v1[3] * v1[3])); }
;             ss += __shfl_xor(ss, 16); ss += __shfl_xor(ss, 32);
;             if (fq == 0) (void)__hip_atomic_fetch_add((unsigned*)(ssq_out + row), (unsigned)(ss * SSQ_SCALE + 0.5f), __ATOMIC_RELAXED, __HIP_MEMORY_SCOPE_AGENT);
.LBB0_170:
	v_lshl_add_u32 v160, s45, 8, v184
	v_lshl_or_b32 v158, s50, 8, v186
	v_ashrrev_i32_e32 v161, 31, v160
	v_ashrrev_i32_e32 v159, 31, v158
	v_lshlrev_b64 v[132:133], 12, v[160:161]
	v_lshl_add_u64 v[132:133], s[46:47], 0, v[132:133]
	v_lshlrev_b64 v[134:135], 1, v[158:159]
	v_lshl_add_u64 v[166:167], v[132:133], 0, v[134:135]
	global_load_dwordx4 v[188:191], v[166:167], off
	global_load_dwordx4 v[192:195], v[166:167], off offset:256
	v_or_b32_e32 v162, 16, v160
	v_ashrrev_i32_e32 v163, 31, v162
	v_lshlrev_b64 v[132:133], 12, v[162:163]
	v_lshl_add_u64 v[132:133], s[46:47], 0, v[132:133]
	v_lshl_add_u64 v[164:165], v[132:133], 0, v[134:135]
	global_load_dwordx4 v[136:139], v[164:165], off
	global_load_dwordx4 v[132:135], v[164:165], off offset:256
	s_mov_b64 s[14:15], 0x20000
	v_lshl_add_u64 v[248:249], v[166:167], 0, s[14:15]
	global_load_dwordx4 v[200:203], v[248:249], off
	global_load_dwordx4 v[204:207], v[248:249], off offset:256
	s_mov_b64 s[14:15], 0x30000
	v_lshl_add_u64 v[248:249], v[166:167], 0, s[14:15]
	global_load_dwordx4 v[208:211], v[248:249], off
	global_load_dwordx4 v[212:215], v[248:249], off offset:256
	s_mov_b64 s[14:15], 0x80000
	v_lshl_add_u64 v[248:249], v[166:167], 0, s[14:15]
	global_load_dwordx4 v[216:219], v[248:249], off
	global_load_dwordx4 v[220:223], v[248:249], off offset:256
	s_mov_b64 s[14:15], 0x90000
	v_lshl_add_u64 v[248:249], v[166:167], 0, s[14:15]
	global_load_dwordx4 v[224:227], v[248:249], off
	global_load_dwordx4 v[228:231], v[248:249], off offset:256
	s_mov_b64 s[14:15], 0xa0000
	v_lshl_add_u64 v[248:249], v[166:167], 0, s[14:15]
	global_load_dwordx4 v[232:235], v[248:249], off
	global_load_dwordx4 v[236:239], v[248:249], off offset:256
	s_mov_b64 s[14:15], 0xb0000
	v_lshl_add_u64 v[248:249], v[166:167], 0, s[14:15]
	global_load_dwordx4 v[240:243], v[248:249], off
	global_load_dwordx4 v[244:247], v[248:249], off offset:256
	s_waitcnt vmcnt(14)
	v_lshlrev_b32_e32 v196, 16, v188
	v_and_b32_e32 v197, 0xffff0000, v188
	v_lshlrev_b32_e32 v188, 16, v189
	v_and_b32_e32 v189, 0xffff0000, v189
	v_lshlrev_b32_e32 v198, 16, v190
	v_and_b32_e32 v199, 0xffff0000, v190
	v_lshlrev_b32_e32 v190, 16, v191
	v_and_b32_e32 v191, 0xffff0000, v191
	v_pk_fma_f32 v[130:131], v[130:131], 0.5, v[188:189] op_sel_hi:[1,0,1]
	v_pk_fma_f32 v[128:129], v[128:129], 0.5, v[196:197] op_sel_hi:[1,0,1]
	v_pk_fma_f32 v[188:189], v[124:125], 0.5, v[198:199] op_sel_hi:[1,0,1]
	v_cvt_pk_bf16_f32 v124, v128, v129
	v_cvt_pk_bf16_f32 v125, v130, v131
	v_pk_fma_f32 v[190:191], v[126:127], 0.5, v[190:191] op_sel_hi:[1,0,1]
	v_cvt_pk_bf16_f32 v126, v188, v189
	s_nop 0
	v_cvt_pk_bf16_f32 v127, v190, v191
	global_store_dwordx4 v[166:167], v[124:127], off
	s_nop 1
	v_mul_f32_e32 v124, v128, v128
	v_mul_f32_e32 v125, v130, v130
	v_fmac_f32_e32 v124, v129, v129
	v_fmac_f32_e32 v125, v131, v131
	v_add_f32_e32 v124, v125, v124
	v_mul_f32_e32 v125, v188, v188
	v_mul_f32_e32 v126, v191, v191
	v_fmac_f32_e32 v125, v189, v189
	v_fmac_f32_e32 v126, v190, v190
	v_add_f32_e32 v125, v126, v125
	v_add_f32_e32 v188, v125, v124
	v_lshlrev_b32_e32 v124, 16, v192
	v_and_b32_e32 v125, 0xffff0000, v192
	v_lshlrev_b32_e32 v126, 16, v193
	v_and_b32_e32 v127, 0xffff0000, v193
	v_lshlrev_b32_e32 v128, 16, v194
	v_and_b32_e32 v129, 0xffff0000, v194
	v_lshlrev_b32_e32 v130, 16, v195
	v_and_b32_e32 v131, 0xffff0000, v195
	v_pk_fma_f32 v[122:123], v[122:123], 0.5, v[126:127] op_sel_hi:[1,0,1]
	v_pk_fma_f32 v[120:121], v[120:121], 0.5, v[124:125] op_sel_hi:[1,0,1]
	v_pk_fma_f32 v[124:125], v[116:117], 0.5, v[128:129] op_sel_hi:[1,0,1]
	v_cvt_pk_bf16_f32 v116, v120, v121
	v_cvt_pk_bf16_f32 v117, v122, v123
	v_pk_fma_f32 v[126:127], v[118:119], 0.5, v[130:131] op_sel_hi:[1,0,1]
	v_cvt_pk_bf16_f32 v118, v124, v125
	s_nop 0
	v_cvt_pk_bf16_f32 v119, v126, v127
	global_store_dwordx4 v[166:167], v[116:119], off offset:256
	s_nop 1
	v_mul_f32_e32 v116, v120, v120
	v_mul_f32_e32 v117, v122, v122
	v_fmac_f32_e32 v116, v121, v121
	v_fmac_f32_e32 v117, v123, v123
	v_add_f32_e32 v116, v117, v116
	v_mul_f32_e32 v117, v124, v124
	v_mul_f32_e32 v118, v127, v127
	v_fmac_f32_e32 v117, v125, v125
	v_fmac_f32_e32 v118, v126, v126
	v_add_f32_e32 v117, v118, v117
	v_and_b32_e32 v118, 64, v169
	v_add_f32_e32 v116, v117, v116
	v_xor_b32_e32 v117, 16, v169
	v_add_u32_e32 v118, 64, v118
	v_cmp_lt_i32_e32 vcc, v117, v118
	v_add_f32_e32 v116, v188, v116
	s_nop 0
	v_cndmask_b32_e32 v117, v169, v117, vcc
	v_lshlrev_b32_e32 v128, 2, v117
	ds_bpermute_b32 v117, v128, v116
	s_waitcnt lgkmcnt(0)
	v_add_f32_e32 v116, v116, v117
	v_xor_b32_e32 v117, 32, v169
	v_cmp_lt_i32_e32 vcc, v117, v118
	s_nop 1
	v_cndmask_b32_e32 v117, v169, v117, vcc
	v_lshlrev_b32_e32 v129, 2, v117
	ds_bpermute_b32 v117, v129, v116
	s_and_saveexec_b64 s[14:15], s[2:3]
	s_cbranch_execz .LBB0_172
	s_waitcnt lgkmcnt(0)
	v_add_f32_e32 v116, v116, v117
	v_fma_f32 v116, v116, s60, 0.5
	v_cvt_u32_f32_e32 v118, v116
	v_lshl_add_u64 v[116:117], v[160:161], 2, s[8:9]
	global_atomic_add v[116:117], v118, off
; __device__ __forceinline__ unsigned cvt_pk_bf16(float lo, float hi) { unsigned r; asm volatile("v_cvt_pk_bf16_f32 %0, %1, %2" : "=v"(r) : "v"(lo), "v"(hi)); return r; }
;     __device__ __forceinline__ void operator()(const f32x4 (&acc)[2][2][4][2], const Unit& u, int wr, int wc, int fr, int fq, const float (&)[8]) const {
;     ...
;         for (int g = 0; g < 8; ++g) { const int ai = g >> 2, m = g & 3, row = row0 + ai * HALF + m * 16; const size_t off = (size_t)row * 2048 + col0; float ss = 0.f;
;             if (g + 1 < 8) { const size_t offn = (size_t)(row0 + ((g + 1) >> 2) * HALF + ((g + 1) & 3) * 16) * 2048 + col0;
; #pragma unroll
;                 for (int bj = 0; bj < 2; ++bj) xn[bj] = *(const u32x4*)(xb + offn + bj * HALF); }
; #pragma unroll
;             for (int bj = 0; bj < 2; ++bj) { const size_t o = off + bj * HALF; const u32x4 xw = xc[bj];
;                 const f32x4 x0 = (f32x4){__uint_as_float(xw.x << 16), __uint_as_float(xw.x & 0xffff0000u), __uint_as_float(xw.y << 16), __uint_as_float(xw.y & 0xffff0000u)};
;                 const f32x4 x1 = (f32x4){__uint_as_float(xw.z << 16), __uint_as_float(xw.z & 0xffff0000u), __uint_as_float(xw.w << 16), __uint_as_float(xw.w & 0xffff0000u)};
;                 const f32x4 v0 = x0 + acc[ai][bj][m][0] * alpha, v1 = x1 + acc[ai][bj][m][1] * alpha;
;                 if (xf) { *(f32x4*)(xf + o) = v0; *(f32x4*)(xf + o + 4) = v1; }
;                 else { u32x4 w; w.x = cvt_pk_bf16(v0[0], v0[1]); w.y = cvt_pk_bf16(v0[2], v0[3]); w.z = cvt_pk_bf16(v1[0], v1[1]); w.w = cvt_pk_bf16(v1[2], v1[3]); *(u32x4*)(xb + o) = w; }
;                 ss += ((v0[0] * v0[0] + v0[1] * v0[1]) + (v0[2] * v0[2] + v0[3] * v0[3])) + ((v1[0] * v1[0] + v1[1] * v1[1]) + (v1[2] * v1[2] + v1[3] * v1[3])); }
;             ss += __shfl_xor(ss, 16); ss += __shfl_xor(ss, 32);
;             if (fq == 0) (void)__hip_atomic_fetch_add((unsigned*)(ssq_out + row), (unsigned)(ss * SSQ_SCALE + 0.5f), __ATOMIC_RELAXED, __HIP_MEMORY_SCOPE_AGENT);
.LBB0_172:
	s_or_b64 exec, exec, s[14:15]
	v_or_b32_e32 v124, 32, v160
	v_ashrrev_i32_e32 v125, 31, v124
	s_waitcnt lgkmcnt(0)
	v_lshlrev_b64 v[116:117], 12, v[124:125]
	v_lshl_add_u64 v[116:117], s[46:47], 0, v[116:117]
	v_lshl_add_u64 v[126:127], v[158:159], 1, v[116:117]
	s_waitcnt vmcnt(12)
	v_mov_b32_e32 v120, v200
	v_mov_b32_e32 v121, v201
	v_mov_b32_e32 v122, v202
	v_mov_b32_e32 v123, v203
	v_mov_b32_e32 v116, v204
	v_mov_b32_e32 v117, v205
	v_mov_b32_e32 v118, v206
	v_mov_b32_e32 v119, v207
	v_lshlrev_b32_e32 v130, 16, v136
	v_and_b32_e32 v131, 0xffff0000, v136
	v_lshlrev_b32_e32 v136, 16, v137
	v_and_b32_e32 v137, 0xffff0000, v137
	v_lshlrev_b32_e32 v166, 16, v138
	v_and_b32_e32 v167, 0xffff0000, v138
	v_lshlrev_b32_e32 v138, 16, v139
	v_and_b32_e32 v139, 0xffff0000, v139
	v_pk_fma_f32 v[114:115], v[114:115], 0.5, v[136:137] op_sel_hi:[1,0,1]
	v_pk_fma_f32 v[112:113], v[112:113], 0.5, v[130:131] op_sel_hi:[1,0,1]
	v_pk_fma_f32 v[136:137], v[110:111], 0.5, v[138:139] op_sel_hi:[1,0,1]
	v_mul_f32_e32 v110, v112, v112
	v_mul_f32_e32 v111, v114, v114
	v_pk_fma_f32 v[130:131], v[108:109], 0.5, v[166:167] op_sel_hi:[1,0,1]
	v_fmac_f32_e32 v110, v113, v113
	v_fmac_f32_e32 v111, v115, v115
	v_cvt_pk_bf16_f32 v108, v112, v113
	v_add_f32_e32 v110, v111, v110
	v_mul_f32_e32 v111, v130, v130
	v_mul_f32_e32 v112, v137, v137
	v_fmac_f32_e32 v111, v131, v131
	v_fmac_f32_e32 v112, v136, v136
	v_add_f32_e32 v111, v112, v111
	v_add_f32_e32 v138, v111, v110
	v_lshlrev_b32_e32 v110, 16, v132
	v_and_b32_e32 v111, 0xffff0000, v132
	v_lshlrev_b32_e32 v112, 16, v133
	v_and_b32_e32 v113, 0xffff0000, v133
	v_cvt_pk_bf16_f32 v109, v114, v115
	v_lshlrev_b32_e32 v114, 16, v134
	v_and_b32_e32 v115, 0xffff0000, v134
	v_pk_fma_f32 v[106:107], v[106:107], 0.5, v[112:113] op_sel_hi:[1,0,1]
	v_pk_fma_f32 v[104:105], v[104:105], 0.5, v[110:111] op_sel_hi:[1,0,1]
	v_lshlrev_b32_e32 v132, 16, v135
	v_and_b32_e32 v133, 0xffff0000, v135
	v_pk_fma_f32 v[112:113], v[100:101], 0.5, v[114:115] op_sel_hi:[1,0,1]
	v_mul_f32_e32 v100, v104, v104
	v_mul_f32_e32 v101, v106, v106
	v_pk_fma_f32 v[114:115], v[102:103], 0.5, v[132:133] op_sel_hi:[1,0,1]
	v_fmac_f32_e32 v100, v105, v105
	v_fmac_f32_e32 v101, v107, v107
	v_add_f32_e32 v100, v101, v100
	v_mul_f32_e32 v101, v112, v112
	v_mul_f32_e32 v102, v115, v115
	v_fmac_f32_e32 v101, v113, v113
	v_fmac_f32_e32 v102, v114, v114
	v_add_f32_e32 v101, v102, v101
	v_add_f32_e32 v100, v101, v100
	v_add_f32_e32 v100, v138, v100
	ds_bpermute_b32 v101, v128, v100
	v_cvt_pk_bf16_f32 v110, v130, v131
	v_cvt_pk_bf16_f32 v111, v136, v137
	global_store_dwordx4 v[164:165], v[108:111], off
	v_cvt_pk_bf16_f32 v102, v104, v105
	s_waitcnt lgkmcnt(0)
	v_add_f32_e32 v100, v100, v101
	ds_bpermute_b32 v101, v129, v100
	v_cvt_pk_bf16_f32 v103, v106, v107
	v_cvt_pk_bf16_f32 v104, v112, v113
	v_cvt_pk_bf16_f32 v105, v114, v115
	global_store_dwordx4 v[164:165], v[102:105], off offset:256
	s_and_saveexec_b64 s[14:15], s[2:3]
	s_cbranch_execz .LBB0_174
	s_waitcnt lgkmcnt(0)
	v_add_f32_e32 v100, v100, v101
	v_fma_f32 v100, v100, s60, 0.5
	v_cvt_u32_f32_e32 v102, v100
	v_lshl_add_u64 v[100:101], v[162:163], 2, s[8:9]
	global_atomic_add v[100:101], v102, off
.LBB0_174:
	s_or_b64 exec, exec, s[14:15]
	v_or_b32_e32 v108, 48, v160
	v_ashrrev_i32_e32 v109, 31, v108
	s_waitcnt lgkmcnt(0)
	v_lshlrev_b64 v[100:101], 12, v[108:109]
	v_lshl_add_u64 v[100:101], s[46:47], 0, v[100:101]
	v_lshl_add_u64 v[110:111], v[158:159], 1, v[100:101]
	s_waitcnt vmcnt(12)
	v_mov_b32_e32 v104, v208
	v_mov_b32_e32 v105, v209
	v_mov_b32_e32 v106, v210
	v_mov_b32_e32 v107, v211
	v_mov_b32_e32 v100, v212
	v_mov_b32_e32 v101, v213
	v_mov_b32_e32 v102, v214
	v_mov_b32_e32 v103, v215
	v_lshlrev_b32_e32 v112, 16, v120
	v_and_b32_e32 v113, 0xffff0000, v120
	v_lshlrev_b32_e32 v114, 16, v121
	v_and_b32_e32 v115, 0xffff0000, v121
	v_lshlrev_b32_e32 v120, 16, v122
	v_and_b32_e32 v121, 0xffff0000, v122
	v_lshlrev_b32_e32 v122, 16, v123
	v_and_b32_e32 v123, 0xffff0000, v123
	v_pk_fma_f32 v[98:99], v[98:99], 0.5, v[114:115] op_sel_hi:[1,0,1]
	v_pk_fma_f32 v[96:97], v[96:97], 0.5, v[112:113] op_sel_hi:[1,0,1]
	v_pk_fma_f32 v[114:115], v[94:95], 0.5, v[122:123] op_sel_hi:[1,0,1]
	v_mul_f32_e32 v94, v96, v96
	v_mul_f32_e32 v95, v98, v98
	v_pk_fma_f32 v[112:113], v[92:93], 0.5, v[120:121] op_sel_hi:[1,0,1]
	v_fmac_f32_e32 v94, v97, v97
	v_fmac_f32_e32 v95, v99, v99
	v_cvt_pk_bf16_f32 v92, v96, v97
	v_add_f32_e32 v94, v95, v94
	v_mul_f32_e32 v95, v112, v112
	v_mul_f32_e32 v96, v115, v115
	v_fmac_f32_e32 v95, v113, v113
	v_fmac_f32_e32 v96, v114, v114
	v_add_f32_e32 v95, v96, v95
	v_add_f32_e32 v120, v95, v94
	v_lshlrev_b32_e32 v94, 16, v116
	v_and_b32_e32 v95, 0xffff0000, v116
	v_lshlrev_b32_e32 v96, 16, v117
	v_and_b32_e32 v97, 0xffff0000, v117
	v_cvt_pk_bf16_f32 v93, v98, v99
	v_lshlrev_b32_e32 v98, 16, v118
	v_and_b32_e32 v99, 0xffff0000, v118
	v_pk_fma_f32 v[90:91], v[90:91], 0.5, v[96:97] op_sel_hi:[1,0,1]
	v_pk_fma_f32 v[88:89], v[88:89], 0.5, v[94:95] op_sel_hi:[1,0,1]
	v_lshlrev_b32_e32 v116, 16, v119
	v_and_b32_e32 v117, 0xffff0000, v119
	v_pk_fma_f32 v[96:97], v[84:85], 0.5, v[98:99] op_sel_hi:[1,0,1]
	v_mul_f32_e32 v84, v88, v88
	v_mul_f32_e32 v85, v90, v90
	v_pk_fma_f32 v[98:99], v[86:87], 0.5, v[116:117] op_sel_hi:[1,0,1]
	v_fmac_f32_e32 v84, v89, v89
	v_fmac_f32_e32 v85, v91, v91
	v_add_f32_e32 v84, v85, v84
	v_mul_f32_e32 v85, v96, v96
	v_mul_f32_e32 v86, v99, v99
	v_fmac_f32_e32 v85, v97, v97
	v_fmac_f32_e32 v86, v98, v98
	v_add_f32_e32 v85, v86, v85
	v_add_f32_e32 v84, v85, v84
	v_add_f32_e32 v84, v120, v84
	ds_bpermute_b32 v85, v128, v84
	v_cvt_pk_bf16_f32 v94, v112, v113
	v_cvt_pk_bf16_f32 v95, v114, v115
	global_store_dwordx4 v[126:127], v[92:95], off
	v_cvt_pk_bf16_f32 v86, v88, v89
	s_waitcnt lgkmcnt(0)
	v_add_f32_e32 v84, v84, v85
	ds_bpermute_b32 v85, v129, v84
	v_cvt_pk_bf16_f32 v87, v90, v91
	v_cvt_pk_bf16_f32 v88, v96, v97
	v_cvt_pk_bf16_f32 v89, v98, v99
	global_store_dwordx4 v[126:127], v[86:89], off offset:256
	s_and_saveexec_b64 s[14:15], s[2:3]
	s_cbranch_execz .LBB0_176
	s_waitcnt lgkmcnt(0)
	v_add_f32_e32 v84, v84, v85
	v_fma_f32 v84, v84, s60, 0.5
	v_cvt_u32_f32_e32 v86, v84
	v_lshl_add_u64 v[84:85], v[124:125], 2, s[8:9]
	global_atomic_add v[84:85], v86, off
; __device__ __forceinline__ unsigned cvt_pk_bf16(float lo, float hi) { unsigned r; asm volatile("v_cvt_pk_bf16_f32 %0, %1, %2" : "=v"(r) : "v"(lo), "v"(hi)); return r; }
;     __device__ __forceinline__ void operator()(const f32x4 (&acc)[2][2][4][2], const Unit& u, int wr, int wc, int fr, int fq, const float (&)[8]) const {
;     ...
;         for (int g = 0; g < 8; ++g) { const int ai = g >> 2, m = g & 3, row = row0 + ai * HALF + m * 16; const size_t off = (size_t)row * 2048 + col0; float ss = 0.f;
;             if (g + 1 < 8) { const size_t offn = (size_t)(row0 + ((g + 1) >> 2) * HALF + ((g + 1) & 3) * 16) * 2048 + col0;
; #pragma unroll
;                 for (int bj = 0; bj < 2; ++bj) xn[bj] = *(const u32x4*)(xb + offn + bj * HALF); }
; #pragma unroll
;             for (int bj = 0; bj < 2; ++bj) { const size_t o = off + bj * HALF; const u32x4 xw = xc[bj];
;                 const f32x4 x0 = (f32x4){__uint_as_float(xw.x << 16), __uint_as_float(xw.x & 0xffff0000u), __uint_as_float(xw.y << 16), __uint_as_float(xw.y & 0xffff0000u)};
;                 const f32x4 x1 = (f32x4){__uint_as_float(xw.z << 16), __uint_as_float(xw.z & 0xffff0000u), __uint_as_float(xw.w << 16), __uint_as_float(xw.w & 0xffff0000u)};
;                 const f32x4 v0 = x0 + acc[ai][bj][m][0] * alpha, v1 = x1 + acc[ai][bj][m][1] * alpha;
;                 if (xf) { *(f32x4*)(xf + o) = v0; *(f32x4*)(xf + o + 4) = v1; }
;                 else { u32x4 w; w.x = cvt_pk_bf16(v0[0], v0[1]); w.y = cvt_pk_bf16(v0[2], v0[3]); w.z = cvt_pk_bf16(v1[0], v1[1]); w.w = cvt_pk_bf16(v1[2], v1[3]); *(u32x4*)(xb + o) = w; }
;                 ss += ((v0[0] * v0[0] + v0[1] * v0[1]) + (v0[2] * v0[2] + v0[3] * v0[3])) + ((v1[0] * v1[0] + v1[1] * v1[1]) + (v1[2] * v1[2] + v1[3] * v1[3])); }
;             ss += __shfl_xor(ss, 16); ss += __shfl_xor(ss, 32);
;             if (fq == 0) (void)__hip_atomic_fetch_add((unsigned*)(ssq_out + row), (unsigned)(ss * SSQ_SCALE + 0.5f), __ATOMIC_RELAXED, __HIP_MEMORY_SCOPE_AGENT);
; #pragma unroll
;             for (int bj = 0; bj < 2; ++bj) xc[bj] = xn[bj]; }
.LBB0_176:
	s_or_b64 exec, exec, s[14:15]
	v_add_u32_e32 v92, 0x80, v160
	v_ashrrev_i32_e32 v93, 31, v92
	s_waitcnt lgkmcnt(0)
	v_lshlrev_b64 v[84:85], 12, v[92:93]
	v_lshl_add_u64 v[84:85], s[46:47], 0, v[84:85]
	v_lshl_add_u64 v[94:95], v[158:159], 1, v[84:85]
	s_waitcnt vmcnt(12)
	v_mov_b32_e32 v88, v216
	v_mov_b32_e32 v89, v217
	v_mov_b32_e32 v90, v218
	v_mov_b32_e32 v91, v219
	v_mov_b32_e32 v84, v220
	v_mov_b32_e32 v85, v221
	v_mov_b32_e32 v86, v222
	v_mov_b32_e32 v87, v223
	v_lshlrev_b32_e32 v96, 16, v104
	v_and_b32_e32 v97, 0xffff0000, v104
	v_lshlrev_b32_e32 v98, 16, v105
	v_and_b32_e32 v99, 0xffff0000, v105
	v_lshlrev_b32_e32 v104, 16, v106
	v_and_b32_e32 v105, 0xffff0000, v106
	v_lshlrev_b32_e32 v106, 16, v107
	v_and_b32_e32 v107, 0xffff0000, v107
	v_pk_fma_f32 v[82:83], v[82:83], 0.5, v[98:99] op_sel_hi:[1,0,1]
	v_pk_fma_f32 v[80:81], v[80:81], 0.5, v[96:97] op_sel_hi:[1,0,1]
	v_pk_fma_f32 v[98:99], v[78:79], 0.5, v[106:107] op_sel_hi:[1,0,1]
	v_mul_f32_e32 v78, v80, v80
	v_mul_f32_e32 v79, v82, v82
	v_pk_fma_f32 v[96:97], v[76:77], 0.5, v[104:105] op_sel_hi:[1,0,1]
	v_fmac_f32_e32 v78, v81, v81
	v_fmac_f32_e32 v79, v83, v83
	v_cvt_pk_bf16_f32 v76, v80, v81
	v_add_f32_e32 v78, v79, v78
	v_mul_f32_e32 v79, v96, v96
	v_mul_f32_e32 v80, v99, v99
	v_fmac_f32_e32 v79, v97, v97
	v_fmac_f32_e32 v80, v98, v98
	v_add_f32_e32 v79, v80, v79
	v_add_f32_e32 v104, v79, v78
	v_lshlrev_b32_e32 v78, 16, v100
	v_and_b32_e32 v79, 0xffff0000, v100
	v_lshlrev_b32_e32 v80, 16, v101
	v_and_b32_e32 v81, 0xffff0000, v101
	v_cvt_pk_bf16_f32 v77, v82, v83
	v_lshlrev_b32_e32 v82, 16, v102
	v_and_b32_e32 v83, 0xffff0000, v102
	v_pk_fma_f32 v[74:75], v[74:75], 0.5, v[80:81] op_sel_hi:[1,0,1]
	v_pk_fma_f32 v[72:73], v[72:73], 0.5, v[78:79] op_sel_hi:[1,0,1]
	v_lshlrev_b32_e32 v100, 16, v103
	v_and_b32_e32 v101, 0xffff0000, v103
	v_pk_fma_f32 v[80:81], v[68:69], 0.5, v[82:83] op_sel_hi:[1,0,1]
	v_mul_f32_e32 v68, v72, v72
	v_mul_f32_e32 v69, v74, v74
	v_pk_fma_f32 v[82:83], v[70:71], 0.5, v[100:101] op_sel_hi:[1,0,1]
	v_fmac_f32_e32 v68, v73, v73
	v_fmac_f32_e32 v69, v75, v75
	v_add_f32_e32 v68, v69, v68
	v_mul_f32_e32 v69, v80, v80
	v_mul_f32_e32 v70, v83, v83
	v_fmac_f32_e32 v69, v81, v81
	v_fmac_f32_e32 v70, v82, v82
	v_add_f32_e32 v69, v70, v69
	v_add_f32_e32 v68, v69, v68
	v_add_f32_e32 v68, v104, v68
	ds_bpermute_b32 v69, v128, v68
	v_cvt_pk_bf16_f32 v78, v96, v97
	v_cvt_pk_bf16_f32 v79, v98, v99
	global_store_dwordx4 v[110:111], v[76:79], off
	v_cvt_pk_bf16_f32 v70, v72, v73
	s_waitcnt lgkmcnt(0)
	v_add_f32_e32 v68, v68, v69
	ds_bpermute_b32 v69, v129, v68
	v_cvt_pk_bf16_f32 v71, v74, v75
	v_cvt_pk_bf16_f32 v72, v80, v81
	v_cvt_pk_bf16_f32 v73, v82, v83
	global_store_dwordx4 v[110:111], v[70:73], off offset:256
	s_and_saveexec_b64 s[14:15], s[2:3]
	s_cbranch_execz .LBB0_178
	s_waitcnt lgkmcnt(0)
	v_add_f32_e32 v68, v68, v69
	v_fma_f32 v68, v68, s60, 0.5
	v_cvt_u32_f32_e32 v70, v68
	v_lshl_add_u64 v[68:69], v[108:109], 2, s[8:9]
	global_atomic_add v[68:69], v70, off
.LBB0_178:
	s_or_b64 exec, exec, s[14:15]
	v_or_b32_e32 v76, 16, v92
	v_ashrrev_i32_e32 v77, 31, v76
	s_waitcnt lgkmcnt(0)
	v_lshlrev_b64 v[68:69], 12, v[76:77]
	v_lshl_add_u64 v[68:69], s[46:47], 0, v[68:69]
	v_lshl_add_u64 v[78:79], v[158:159], 1, v[68:69]
	s_waitcnt vmcnt(12)
	v_mov_b32_e32 v72, v224
	v_mov_b32_e32 v73, v225
	v_mov_b32_e32 v74, v226
	v_mov_b32_e32 v75, v227
	v_mov_b32_e32 v68, v228
	v_mov_b32_e32 v69, v229
	v_mov_b32_e32 v70, v230
	v_mov_b32_e32 v71, v231
	v_lshlrev_b32_e32 v80, 16, v88
	v_and_b32_e32 v81, 0xffff0000, v88
	v_lshlrev_b32_e32 v82, 16, v89
	v_and_b32_e32 v83, 0xffff0000, v89
	v_lshlrev_b32_e32 v88, 16, v90
	v_and_b32_e32 v89, 0xffff0000, v90
	v_lshlrev_b32_e32 v90, 16, v91
	v_and_b32_e32 v91, 0xffff0000, v91
	v_pk_fma_f32 v[66:67], v[66:67], 0.5, v[82:83] op_sel_hi:[1,0,1]
	v_pk_fma_f32 v[64:65], v[64:65], 0.5, v[80:81] op_sel_hi:[1,0,1]
	v_pk_fma_f32 v[82:83], v[62:63], 0.5, v[90:91] op_sel_hi:[1,0,1]
	v_mul_f32_e32 v62, v64, v64
	v_mul_f32_e32 v63, v66, v66
	v_pk_fma_f32 v[80:81], v[60:61], 0.5, v[88:89] op_sel_hi:[1,0,1]
	v_fmac_f32_e32 v62, v65, v65
	v_fmac_f32_e32 v63, v67, v67
	v_cvt_pk_bf16_f32 v60, v64, v65
	v_add_f32_e32 v62, v63, v62
	v_mul_f32_e32 v63, v80, v80
	v_mul_f32_e32 v64, v83, v83
	v_fmac_f32_e32 v63, v81, v81
	v_fmac_f32_e32 v64, v82, v82
	v_add_f32_e32 v63, v64, v63
	v_add_f32_e32 v88, v63, v62
	v_lshlrev_b32_e32 v62, 16, v84
	v_and_b32_e32 v63, 0xffff0000, v84
	v_lshlrev_b32_e32 v64, 16, v85
	v_and_b32_e32 v65, 0xffff0000, v85
	v_cvt_pk_bf16_f32 v61, v66, v67
	v_lshlrev_b32_e32 v66, 16, v86
	v_and_b32_e32 v67, 0xffff0000, v86
	v_pk_fma_f32 v[58:59], v[58:59], 0.5, v[64:65] op_sel_hi:[1,0,1]
	v_pk_fma_f32 v[56:57], v[56:57], 0.5, v[62:63] op_sel_hi:[1,0,1]
	v_lshlrev_b32_e32 v84, 16, v87
	v_and_b32_e32 v85, 0xffff0000, v87
	v_pk_fma_f32 v[64:65], v[52:53], 0.5, v[66:67] op_sel_hi:[1,0,1]
	v_mul_f32_e32 v52, v56, v56
	v_mul_f32_e32 v53, v58, v58
	v_pk_fma_f32 v[66:67], v[54:55], 0.5, v[84:85] op_sel_hi:[1,0,1]
	v_fmac_f32_e32 v52, v57, v57
	v_fmac_f32_e32 v53, v59, v59
	v_add_f32_e32 v52, v53, v52
	v_mul_f32_e32 v53, v64, v64
	v_mul_f32_e32 v54, v67, v67
	v_fmac_f32_e32 v53, v65, v65
	v_fmac_f32_e32 v54, v66, v66
	v_add_f32_e32 v53, v54, v53
	v_add_f32_e32 v52, v53, v52
	v_add_f32_e32 v52, v88, v52
	ds_bpermute_b32 v53, v128, v52
	v_cvt_pk_bf16_f32 v62, v80, v81
	v_cvt_pk_bf16_f32 v63, v82, v83
	global_store_dwordx4 v[94:95], v[60:63], off
	v_cvt_pk_bf16_f32 v54, v56, v57
	s_waitcnt lgkmcnt(0)
	v_add_f32_e32 v52, v52, v53
	ds_bpermute_b32 v53, v129, v52
	v_cvt_pk_bf16_f32 v55, v58, v59
	v_cvt_pk_bf16_f32 v56, v64, v65
	v_cvt_pk_bf16_f32 v57, v66, v67
	global_store_dwordx4 v[94:95], v[54:57], off offset:256
	s_and_saveexec_b64 s[14:15], s[2:3]
	s_cbranch_execz .LBB0_180
	s_waitcnt lgkmcnt(0)
	v_add_f32_e32 v52, v52, v53
	v_fma_f32 v52, v52, s60, 0.5
	v_cvt_u32_f32_e32 v54, v52
	v_lshl_add_u64 v[52:53], v[92:93], 2, s[8:9]
	global_atomic_add v[52:53], v54, off
; __device__ __forceinline__ unsigned cvt_pk_bf16(float lo, float hi) { unsigned r; asm volatile("v_cvt_pk_bf16_f32 %0, %1, %2" : "=v"(r) : "v"(lo), "v"(hi)); return r; }
;     __device__ __forceinline__ void operator()(const f32x4 (&acc)[2][2][4][2], const Unit& u, int wr, int wc, int fr, int fq, const float (&)[8]) const {
;     ...
;         for (int g = 0; g < 8; ++g) { const int ai = g >> 2, m = g & 3, row = row0 + ai * HALF + m * 16; const size_t off = (size_t)row * 2048 + col0; float ss = 0.f;
;             if (g + 1 < 8) { const size_t offn = (size_t)(row0 + ((g + 1) >> 2) * HALF + ((g + 1) & 3) * 16) * 2048 + col0;
; #pragma unroll
;                 for (int bj = 0; bj < 2; ++bj) xn[bj] = *(const u32x4*)(xb + offn + bj * HALF); }
; #pragma unroll
;             for (int bj = 0; bj < 2; ++bj) { const size_t o = off + bj * HALF; const u32x4 xw = xc[bj];
;                 const f32x4 x0 = (f32x4){__uint_as_float(xw.x << 16), __uint_as_float(xw.x & 0xffff0000u), __uint_as_float(xw.y << 16), __uint_as_float(xw.y & 0xffff0000u)};
;                 const f32x4 x1 = (f32x4){__uint_as_float(xw.z << 16), __uint_as_float(xw.z & 0xffff0000u), __uint_as_float(xw.w << 16), __uint_as_float(xw.w & 0xffff0000u)};
;                 const f32x4 v0 = x0 + acc[ai][bj][m][0] * alpha, v1 = x1 + acc[ai][bj][m][1] * alpha;
;                 if (xf) { *(f32x4*)(xf + o) = v0; *(f32x4*)(xf + o + 4) = v1; }
;                 else { u32x4 w; w.x = cvt_pk_bf16(v0[0], v0[1]); w.y = cvt_pk_bf16(v0[2], v0[3]); w.z = cvt_pk_bf16(v1[0], v1[1]); w.w = cvt_pk_bf16(v1[2], v1[3]); *(u32x4*)(xb + o) = w; }
;                 ss += ((v0[0] * v0[0] + v0[1] * v0[1]) + (v0[2] * v0[2] + v0[3] * v0[3])) + ((v1[0] * v1[0] + v1[1] * v1[1]) + (v1[2] * v1[2] + v1[3] * v1[3])); }
;             ss += __shfl_xor(ss, 16); ss += __shfl_xor(ss, 32);
;             if (fq == 0) (void)__hip_atomic_fetch_add((unsigned*)(ssq_out + row), (unsigned)(ss * SSQ_SCALE + 0.5f), __ATOMIC_RELAXED, __HIP_MEMORY_SCOPE_AGENT);
; #pragma unroll
;             for (int bj = 0; bj < 2; ++bj) xc[bj] = xn[bj]; }
.LBB0_180:
	s_or_b64 exec, exec, s[14:15]
	v_or_b32_e32 v60, 32, v92
	v_ashrrev_i32_e32 v61, 31, v60
	s_waitcnt lgkmcnt(0)
	v_lshlrev_b64 v[52:53], 12, v[60:61]
	v_lshl_add_u64 v[52:53], s[46:47], 0, v[52:53]
	v_lshl_add_u64 v[62:63], v[158:159], 1, v[52:53]
	s_waitcnt vmcnt(12)
	v_mov_b32_e32 v56, v232
	v_mov_b32_e32 v57, v233
	v_mov_b32_e32 v58, v234
	v_mov_b32_e32 v59, v235
	v_mov_b32_e32 v52, v236
	v_mov_b32_e32 v53, v237
	v_mov_b32_e32 v54, v238
	v_mov_b32_e32 v55, v239
	v_lshlrev_b32_e32 v64, 16, v72
	v_and_b32_e32 v65, 0xffff0000, v72
	v_lshlrev_b32_e32 v66, 16, v73
	v_and_b32_e32 v67, 0xffff0000, v73
	v_lshlrev_b32_e32 v72, 16, v74
	v_and_b32_e32 v73, 0xffff0000, v74
	v_lshlrev_b32_e32 v74, 16, v75
	v_and_b32_e32 v75, 0xffff0000, v75
	v_pk_fma_f32 v[50:51], v[50:51], 0.5, v[66:67] op_sel_hi:[1,0,1]
	v_pk_fma_f32 v[48:49], v[48:49], 0.5, v[64:65] op_sel_hi:[1,0,1]
	v_pk_fma_f32 v[66:67], v[46:47], 0.5, v[74:75] op_sel_hi:[1,0,1]
	v_mul_f32_e32 v46, v48, v48
	v_mul_f32_e32 v47, v50, v50
	v_pk_fma_f32 v[64:65], v[44:45], 0.5, v[72:73] op_sel_hi:[1,0,1]
	v_fmac_f32_e32 v46, v49, v49
	v_fmac_f32_e32 v47, v51, v51
	v_cvt_pk_bf16_f32 v44, v48, v49
	v_add_f32_e32 v46, v47, v46
	v_mul_f32_e32 v47, v64, v64
	v_mul_f32_e32 v48, v67, v67
	v_fmac_f32_e32 v47, v65, v65
	v_fmac_f32_e32 v48, v66, v66
	v_add_f32_e32 v47, v48, v47
	v_add_f32_e32 v72, v47, v46
	v_lshlrev_b32_e32 v46, 16, v68
	v_and_b32_e32 v47, 0xffff0000, v68
	v_lshlrev_b32_e32 v48, 16, v69
	v_and_b32_e32 v49, 0xffff0000, v69
	v_cvt_pk_bf16_f32 v45, v50, v51
	v_lshlrev_b32_e32 v50, 16, v70
	v_and_b32_e32 v51, 0xffff0000, v70
	v_pk_fma_f32 v[42:43], v[42:43], 0.5, v[48:49] op_sel_hi:[1,0,1]
	v_pk_fma_f32 v[40:41], v[40:41], 0.5, v[46:47] op_sel_hi:[1,0,1]
	v_lshlrev_b32_e32 v68, 16, v71
	v_and_b32_e32 v69, 0xffff0000, v71
	v_pk_fma_f32 v[48:49], v[36:37], 0.5, v[50:51] op_sel_hi:[1,0,1]
	v_mul_f32_e32 v36, v40, v40
	v_mul_f32_e32 v37, v42, v42
	v_pk_fma_f32 v[50:51], v[38:39], 0.5, v[68:69] op_sel_hi:[1,0,1]
	v_fmac_f32_e32 v36, v41, v41
	v_fmac_f32_e32 v37, v43, v43
	v_add_f32_e32 v36, v37, v36
	v_mul_f32_e32 v37, v48, v48
	v_mul_f32_e32 v38, v51, v51
	v_fmac_f32_e32 v37, v49, v49
	v_fmac_f32_e32 v38, v50, v50
	v_add_f32_e32 v37, v38, v37
	v_add_f32_e32 v36, v37, v36
	v_add_f32_e32 v36, v72, v36
	ds_bpermute_b32 v37, v128, v36
	v_cvt_pk_bf16_f32 v46, v64, v65
	v_cvt_pk_bf16_f32 v47, v66, v67
	global_store_dwordx4 v[78:79], v[44:47], off
	v_cvt_pk_bf16_f32 v38, v40, v41
	s_waitcnt lgkmcnt(0)
	v_add_f32_e32 v36, v36, v37
	ds_bpermute_b32 v37, v129, v36
	v_cvt_pk_bf16_f32 v39, v42, v43
	v_cvt_pk_bf16_f32 v40, v48, v49
	v_cvt_pk_bf16_f32 v41, v50, v51
	global_store_dwordx4 v[78:79], v[38:41], off offset:256
	s_and_saveexec_b64 s[14:15], s[2:3]
	s_cbranch_execz .LBB0_182
	s_waitcnt lgkmcnt(0)
	v_add_f32_e32 v36, v36, v37
	v_fma_f32 v36, v36, s60, 0.5
	v_cvt_u32_f32_e32 v38, v36
	v_lshl_add_u64 v[36:37], v[76:77], 2, s[8:9]
	global_atomic_add v[36:37], v38, off
; __device__ __forceinline__ unsigned cvt_pk_bf16(float lo, float hi) { unsigned r; asm volatile("v_cvt_pk_bf16_f32 %0, %1, %2" : "=v"(r) : "v"(lo), "v"(hi)); return r; }
;     __device__ __forceinline__ void operator()(const f32x4 (&acc)[2][2][4][2], const Unit& u, int wr, int wc, int fr, int fq, const float (&)[8]) const {
;     ...
;         for (int g = 0; g < 8; ++g) { const int ai = g >> 2, m = g & 3, row = row0 + ai * HALF + m * 16; const size_t off = (size_t)row * 2048 + col0; float ss = 0.f;
;             if (g + 1 < 8) { const size_t offn = (size_t)(row0 + ((g + 1) >> 2) * HALF + ((g + 1) & 3) * 16) * 2048 + col0;
; #pragma unroll
;                 for (int bj = 0; bj < 2; ++bj) xn[bj] = *(const u32x4*)(xb + offn + bj * HALF); }
; #pragma unroll
;             for (int bj = 0; bj < 2; ++bj) { const size_t o = off + bj * HALF; const u32x4 xw = xc[bj];
;                 const f32x4 x0 = (f32x4){__uint_as_float(xw.x << 16), __uint_as_float(xw.x & 0xffff0000u), __uint_as_float(xw.y << 16), __uint_as_float(xw.y & 0xffff0000u)};
;                 const f32x4 x1 = (f32x4){__uint_as_float(xw.z << 16), __uint_as_float(xw.z & 0xffff0000u), __uint_as_float(xw.w << 16), __uint_as_float(xw.w & 0xffff0000u)};
;                 const f32x4 v0 = x0 + acc[ai][bj][m][0] * alpha, v1 = x1 + acc[ai][bj][m][1] * alpha;
;                 if (xf) { *(f32x4*)(xf + o) = v0; *(f32x4*)(xf + o + 4) = v1; }
;                 else { u32x4 w; w.x = cvt_pk_bf16(v0[0], v0[1]); w.y = cvt_pk_bf16(v0[2], v0[3]); w.z = cvt_pk_bf16(v1[0], v1[1]); w.w = cvt_pk_bf16(v1[2], v1[3]); *(u32x4*)(xb + o) = w; }
;                 ss += ((v0[0] * v0[0] + v0[1] * v0[1]) + (v0[2] * v0[2] + v0[3] * v0[3])) + ((v1[0] * v1[0] + v1[1] * v1[1]) + (v1[2] * v1[2] + v1[3] * v1[3])); }
;             ss += __shfl_xor(ss, 16); ss += __shfl_xor(ss, 32);
;             if (fq == 0) (void)__hip_atomic_fetch_add((unsigned*)(ssq_out + row), (unsigned)(ss * SSQ_SCALE + 0.5f), __ATOMIC_RELAXED, __HIP_MEMORY_SCOPE_AGENT);
; #pragma unroll
;             for (int bj = 0; bj < 2; ++bj) xc[bj] = xn[bj]; }
.LBB0_182:
	s_or_b64 exec, exec, s[14:15]
	v_or_b32_e32 v44, 48, v92
	v_ashrrev_i32_e32 v45, 31, v44
	s_waitcnt lgkmcnt(0)
	v_lshlrev_b64 v[36:37], 12, v[44:45]
	v_lshl_add_u64 v[36:37], s[46:47], 0, v[36:37]
	v_lshl_add_u64 v[46:47], v[158:159], 1, v[36:37]
	s_waitcnt vmcnt(12)
	v_mov_b32_e32 v40, v240
	v_mov_b32_e32 v41, v241
	v_mov_b32_e32 v42, v242
	v_mov_b32_e32 v43, v243
	v_mov_b32_e32 v36, v244
	v_mov_b32_e32 v37, v245
	v_mov_b32_e32 v38, v246
	v_mov_b32_e32 v39, v247
	v_lshlrev_b32_e32 v48, 16, v56
	v_and_b32_e32 v49, 0xffff0000, v56
	v_lshlrev_b32_e32 v50, 16, v57
	v_and_b32_e32 v51, 0xffff0000, v57
	v_lshlrev_b32_e32 v56, 16, v58
	v_and_b32_e32 v57, 0xffff0000, v58
	v_lshlrev_b32_e32 v58, 16, v59
	v_and_b32_e32 v59, 0xffff0000, v59
	v_pk_fma_f32 v[34:35], v[34:35], 0.5, v[50:51] op_sel_hi:[1,0,1]
	v_pk_fma_f32 v[32:33], v[32:33], 0.5, v[48:49] op_sel_hi:[1,0,1]
	v_pk_fma_f32 v[50:51], v[30:31], 0.5, v[58:59] op_sel_hi:[1,0,1]
	v_mul_f32_e32 v30, v32, v32
	v_mul_f32_e32 v31, v34, v34
	v_pk_fma_f32 v[48:49], v[28:29], 0.5, v[56:57] op_sel_hi:[1,0,1]
	v_fmac_f32_e32 v30, v33, v33
	v_fmac_f32_e32 v31, v35, v35
	v_cvt_pk_bf16_f32 v28, v32, v33
	v_add_f32_e32 v30, v31, v30
	v_mul_f32_e32 v31, v48, v48
	v_mul_f32_e32 v32, v51, v51
	v_fmac_f32_e32 v31, v49, v49
	v_fmac_f32_e32 v32, v50, v50
	v_add_f32_e32 v31, v32, v31
	v_add_f32_e32 v56, v31, v30
	v_lshlrev_b32_e32 v30, 16, v52
	v_and_b32_e32 v31, 0xffff0000, v52
	v_lshlrev_b32_e32 v32, 16, v53
	v_and_b32_e32 v33, 0xffff0000, v53
	v_cvt_pk_bf16_f32 v29, v34, v35
	v_lshlrev_b32_e32 v34, 16, v54
	v_and_b32_e32 v35, 0xffff0000, v54
	v_pk_fma_f32 v[26:27], v[26:27], 0.5, v[32:33] op_sel_hi:[1,0,1]
	v_pk_fma_f32 v[24:25], v[24:25], 0.5, v[30:31] op_sel_hi:[1,0,1]
	v_lshlrev_b32_e32 v52, 16, v55
	v_and_b32_e32 v53, 0xffff0000, v55
	v_pk_fma_f32 v[32:33], v[20:21], 0.5, v[34:35] op_sel_hi:[1,0,1]
	v_mul_f32_e32 v20, v24, v24
	v_mul_f32_e32 v21, v26, v26
	v_pk_fma_f32 v[34:35], v[22:23], 0.5, v[52:53] op_sel_hi:[1,0,1]
	v_fmac_f32_e32 v20, v25, v25
	v_fmac_f32_e32 v21, v27, v27
	v_add_f32_e32 v20, v21, v20
	v_mul_f32_e32 v21, v32, v32
	v_mul_f32_e32 v22, v35, v35
	v_fmac_f32_e32 v21, v33, v33
	v_fmac_f32_e32 v22, v34, v34
	v_add_f32_e32 v21, v22, v21
	v_add_f32_e32 v20, v21, v20
	v_add_f32_e32 v20, v56, v20
	ds_bpermute_b32 v21, v128, v20
	v_cvt_pk_bf16_f32 v30, v48, v49
	v_cvt_pk_bf16_f32 v31, v50, v51
	global_store_dwordx4 v[62:63], v[28:31], off
	v_cvt_pk_bf16_f32 v22, v24, v25
	s_waitcnt lgkmcnt(0)
	v_add_f32_e32 v20, v20, v21
	ds_bpermute_b32 v21, v129, v20
	v_cvt_pk_bf16_f32 v23, v26, v27
	v_cvt_pk_bf16_f32 v24, v32, v33
	v_cvt_pk_bf16_f32 v25, v34, v35
	global_store_dwordx4 v[62:63], v[22:25], off offset:256
	s_and_saveexec_b64 s[14:15], s[2:3]
	s_cbranch_execz .LBB0_184
	s_waitcnt lgkmcnt(0)
	v_add_f32_e32 v20, v20, v21
	v_fma_f32 v20, v20, s60, 0.5
	v_cvt_u32_f32_e32 v22, v20
	v_lshl_add_u64 v[20:21], v[60:61], 2, s[8:9]
	global_atomic_add v[20:21], v22, off
.LBB0_184:
	s_or_b64 exec, exec, s[14:15]
	v_lshlrev_b32_e32 v20, 16, v40
	s_waitcnt lgkmcnt(0)
	v_and_b32_e32 v21, 0xffff0000, v40
	v_lshlrev_b32_e32 v22, 16, v41
	v_and_b32_e32 v23, 0xffff0000, v41
	v_lshlrev_b32_e32 v26, 16, v43
	v_and_b32_e32 v27, 0xffff0000, v43
	v_pk_fma_f32 v[18:19], v[18:19], 0.5, v[22:23] op_sel_hi:[1,0,1]
	v_pk_fma_f32 v[16:17], v[16:17], 0.5, v[20:21] op_sel_hi:[1,0,1]
	v_lshlrev_b32_e32 v24, 16, v42
	v_and_b32_e32 v25, 0xffff0000, v42
	v_pk_fma_f32 v[22:23], v[14:15], 0.5, v[26:27] op_sel_hi:[1,0,1]
	v_mul_f32_e32 v14, v16, v16
	v_mul_f32_e32 v15, v18, v18
	v_pk_fma_f32 v[20:21], v[12:13], 0.5, v[24:25] op_sel_hi:[1,0,1]
	v_fmac_f32_e32 v14, v17, v17
	v_fmac_f32_e32 v15, v19, v19
	v_cvt_pk_bf16_f32 v12, v16, v17
	v_add_f32_e32 v14, v15, v14
	v_mul_f32_e32 v15, v20, v20
	v_mul_f32_e32 v16, v23, v23
	v_fmac_f32_e32 v15, v21, v21
	v_fmac_f32_e32 v16, v22, v22
	v_add_f32_e32 v15, v16, v15
	v_add_f32_e32 v26, v15, v14
	v_lshlrev_b32_e32 v14, 16, v36
	v_and_b32_e32 v15, 0xffff0000, v36
	v_lshlrev_b32_e32 v16, 16, v37
	v_and_b32_e32 v17, 0xffff0000, v37
	v_cvt_pk_bf16_f32 v13, v18, v19
	v_lshlrev_b32_e32 v18, 16, v38
	v_and_b32_e32 v19, 0xffff0000, v38
	v_pk_fma_f32 v[10:11], v[10:11], 0.5, v[16:17] op_sel_hi:[1,0,1]
	v_pk_fma_f32 v[8:9], v[8:9], 0.5, v[14:15] op_sel_hi:[1,0,1]
	v_lshlrev_b32_e32 v24, 16, v39
	v_and_b32_e32 v25, 0xffff0000, v39
	v_pk_fma_f32 v[16:17], v[4:5], 0.5, v[18:19] op_sel_hi:[1,0,1]
	v_mul_f32_e32 v4, v8, v8
	v_mul_f32_e32 v5, v10, v10
	v_pk_fma_f32 v[18:19], v[6:7], 0.5, v[24:25] op_sel_hi:[1,0,1]
	v_fmac_f32_e32 v4, v9, v9
	v_fmac_f32_e32 v5, v11, v11
	v_add_f32_e32 v4, v5, v4
	v_mul_f32_e32 v5, v16, v16
	v_mul_f32_e32 v6, v19, v19
	v_fmac_f32_e32 v5, v17, v17
	v_fmac_f32_e32 v6, v18, v18
	v_add_f32_e32 v5, v6, v5
	v_add_f32_e32 v4, v5, v4
	v_add_f32_e32 v4, v26, v4
	ds_bpermute_b32 v5, v128, v4
	v_cvt_pk_bf16_f32 v14, v20, v21
	v_cvt_pk_bf16_f32 v15, v22, v23
	global_store_dwordx4 v[46:47], v[12:15], off
	v_cvt_pk_bf16_f32 v6, v8, v9
	s_waitcnt lgkmcnt(0)
	v_add_f32_e32 v4, v4, v5
	ds_bpermute_b32 v5, v129, v4
	v_cvt_pk_bf16_f32 v7, v10, v11
	v_cvt_pk_bf16_f32 v8, v16, v17
	v_cvt_pk_bf16_f32 v9, v18, v19
	global_store_dwordx4 v[46:47], v[6:9], off offset:256
	s_and_saveexec_b64 s[14:15], s[2:3]
	s_cbranch_execz .LBB0_186
	s_waitcnt lgkmcnt(0)
	v_add_f32_e32 v4, v4, v5
	v_fma_f32 v4, v4, s60, 0.5
	v_cvt_u32_f32_e32 v4, v4
	v_lshl_add_u64 v[6:7], v[44:45], 2, s[8:9]
	global_atomic_add v[6:7], v4, off

; __device__ __forceinline__ unsigned cvt_pk_bf16(float lo, float hi) { unsigned r; asm volatile("v_cvt_pk_bf16_f32 %0, %1, %2" : "=v"(r) : "v"(lo), "v"(hi)); return r; }
;     __device__ __forceinline__ void operator()(const f32x4 (&acc)[2][2][4][2], const Unit& u, int wr, int wc, int fr, int fq, const float (&)[8]) const {
;         const int row0 = u.pm * BM + wr * 64 + fr, col0 = u.pn * BM + wc * 32 + 8 * fq;
;         u32x4 xc[2], xn[2];
;         { const size_t off = (size_t)row0 * 2048 + col0;
; #pragma unroll
;           for (int bj = 0; bj < 2; ++bj) xc[bj] = *(const u32x4*)(xb + off + bj * HALF); }
; #pragma unroll
;         for (int g = 0; g < 8; ++g) { const int ai = g >> 2, m = g & 3, row = row0 + ai * HALF + m * 16; const size_t off = (size_t)row * 2048 + col0; float ss = 0.f;
;             if (g + 1 < 8) { const size_t offn = (size_t)(row0 + ((g + 1) >> 2) * HALF + ((g + 1) & 3) * 16) * 2048 + col0;
; #pragma unroll
;                 for (int bj = 0; bj < 2; ++bj) xn[bj] = *(const u32x4*)(xb + offn + bj * HALF); }
; #pragma unroll
;             for (int bj = 0; bj < 2; ++bj) { const size_t o = off + bj * HALF; const u32x4 xw = xc[bj];
;                 const f32x4 x0 = (f32x4){__uint_as_float(xw.x << 16), __uint_as_float(xw.x & 0xffff0000u), __uint_as_float(xw.y << 16), __uint_as_float(xw.y & 0xffff0000u)};
;                 const f32x4 x1 = (f32x4){__uint_as_float(xw.z << 16), __uint_as_float(xw.z & 0xffff0000u), __uint_as_float(xw.w << 16), __uint_as_float(xw.w & 0xffff0000u)};
;                 const f32x4 v0 = x0 + acc[ai][bj][m][0] * alpha, v1 = x1 + acc[ai][bj][m][1] * alpha;
;                 if (xf) { *(f32x4*)(xf + o) = v0; *(f32x4*)(xf + o + 4) = v1; }
;                 else { u32x4 w; w.x = cvt_pk_bf16(v0[0], v0[1]); w.y = cvt_pk_bf16(v0[2], v0[3]); w.z = cvt_pk_bf16(v1[0], v1[1]); w.w = cvt_pk_bf16(v1[2], v1[3]); *(u32x4*)(xb + o) = w; }
;                 ss += ((v0[0] * v0[0] + v0[1] * v0[1]) + (v0[2] * v0[2] + v0[3] * v0[3])) + ((v1[0] * v1[0] + v1[1] * v1[1]) + (v1[2] * v1[2] + v1[3] * v1[3])); }
;             ss += __shfl_xor(ss, 16); ss += __shfl_xor(ss, 32);
;             if (fq == 0) (void)__hip_atomic_fetch_add((unsigned*)(ssq_out + row), (unsigned)(ss * SSQ_SCALE + 0.5f), __ATOMIC_RELAXED, __HIP_MEMORY_SCOPE_AGENT);
.LBB0_486:
	v_lshl_add_u32 v160, s18, 8, v184
	v_lshl_or_b32 v158, s20, 8, v186
	v_ashrrev_i32_e32 v161, 31, v160
	v_ashrrev_i32_e32 v159, 31, v158
	v_lshlrev_b64 v[132:133], 12, v[160:161]
	v_lshl_add_u64 v[132:133], s[46:47], 0, v[132:133]
	v_lshlrev_b64 v[134:135], 1, v[158:159]
	v_lshl_add_u64 v[166:167], v[132:133], 0, v[134:135]
	global_load_dwordx4 v[188:191], v[166:167], off
	global_load_dwordx4 v[192:195], v[166:167], off offset:256
	v_or_b32_e32 v162, 16, v160
	v_ashrrev_i32_e32 v163, 31, v162
	v_lshlrev_b64 v[132:133], 12, v[162:163]
	v_lshl_add_u64 v[132:133], s[46:47], 0, v[132:133]
	v_lshl_add_u64 v[164:165], v[132:133], 0, v[134:135]
	global_load_dwordx4 v[136:139], v[164:165], off
	global_load_dwordx4 v[132:135], v[164:165], off offset:256
	s_mov_b64 s[18:19], 0x20000
	v_lshl_add_u64 v[248:249], v[166:167], 0, s[18:19]
	global_load_dwordx4 v[200:203], v[248:249], off
	global_load_dwordx4 v[204:207], v[248:249], off offset:256
	s_mov_b64 s[18:19], 0x30000
	v_lshl_add_u64 v[248:249], v[166:167], 0, s[18:19]
	global_load_dwordx4 v[208:211], v[248:249], off
	global_load_dwordx4 v[212:215], v[248:249], off offset:256
	s_mov_b64 s[18:19], 0x80000
	v_lshl_add_u64 v[248:249], v[166:167], 0, s[18:19]
	global_load_dwordx4 v[216:219], v[248:249], off
	global_load_dwordx4 v[220:223], v[248:249], off offset:256
	s_mov_b64 s[18:19], 0x90000
	v_lshl_add_u64 v[248:249], v[166:167], 0, s[18:19]
	global_load_dwordx4 v[224:227], v[248:249], off
	global_load_dwordx4 v[228:231], v[248:249], off offset:256
	s_mov_b64 s[18:19], 0xa0000
	v_lshl_add_u64 v[248:249], v[166:167], 0, s[18:19]
	global_load_dwordx4 v[232:235], v[248:249], off
	global_load_dwordx4 v[236:239], v[248:249], off offset:256
	s_mov_b64 s[18:19], 0xb0000
	v_lshl_add_u64 v[248:249], v[166:167], 0, s[18:19]
	global_load_dwordx4 v[240:243], v[248:249], off
	global_load_dwordx4 v[244:247], v[248:249], off offset:256
	s_waitcnt vmcnt(14)
	v_lshlrev_b32_e32 v196, 16, v188
	v_and_b32_e32 v197, 0xffff0000, v188
	v_lshlrev_b32_e32 v188, 16, v189
	v_and_b32_e32 v189, 0xffff0000, v189
	v_lshlrev_b32_e32 v198, 16, v190
	v_and_b32_e32 v199, 0xffff0000, v190
	v_lshlrev_b32_e32 v190, 16, v191
	v_and_b32_e32 v191, 0xffff0000, v191
	v_pk_add_f32 v[130:131], v[130:131], v[188:189]
	v_pk_add_f32 v[128:129], v[128:129], v[196:197]
	v_pk_add_f32 v[188:189], v[124:125], v[198:199]
	v_cvt_pk_bf16_f32 v124, v128, v129
	v_cvt_pk_bf16_f32 v125, v130, v131
	v_pk_add_f32 v[190:191], v[126:127], v[190:191]
	v_cvt_pk_bf16_f32 v126, v188, v189
	s_nop 0
	v_cvt_pk_bf16_f32 v127, v190, v191
	global_store_dwordx4 v[166:167], v[124:127], off
	s_nop 1
	v_mul_f32_e32 v124, v128, v128
	v_mul_f32_e32 v125, v130, v130
	v_fmac_f32_e32 v124, v129, v129
	v_fmac_f32_e32 v125, v131, v131
	v_add_f32_e32 v124, v125, v124
	v_mul_f32_e32 v125, v188, v188
	v_mul_f32_e32 v126, v191, v191
	v_fmac_f32_e32 v125, v189, v189
	v_fmac_f32_e32 v126, v190, v190
	v_add_f32_e32 v125, v126, v125
	v_add_f32_e32 v188, v125, v124
	v_lshlrev_b32_e32 v124, 16, v192
	v_and_b32_e32 v125, 0xffff0000, v192
	v_lshlrev_b32_e32 v126, 16, v193
	v_and_b32_e32 v127, 0xffff0000, v193
	v_lshlrev_b32_e32 v128, 16, v194
	v_and_b32_e32 v129, 0xffff0000, v194
	v_lshlrev_b32_e32 v130, 16, v195
	v_and_b32_e32 v131, 0xffff0000, v195
	v_pk_add_f32 v[122:123], v[122:123], v[126:127]
	v_pk_add_f32 v[120:121], v[120:121], v[124:125]
	v_pk_add_f32 v[124:125], v[116:117], v[128:129]
	v_cvt_pk_bf16_f32 v116, v120, v121
	v_cvt_pk_bf16_f32 v117, v122, v123
	v_pk_add_f32 v[126:127], v[118:119], v[130:131]
	v_cvt_pk_bf16_f32 v118, v124, v125
	s_nop 0
	v_cvt_pk_bf16_f32 v119, v126, v127
	global_store_dwordx4 v[166:167], v[116:119], off offset:256
	s_nop 1
	v_mul_f32_e32 v116, v120, v120
	v_mul_f32_e32 v117, v122, v122
	v_fmac_f32_e32 v116, v121, v121
	v_fmac_f32_e32 v117, v123, v123
	v_add_f32_e32 v116, v117, v116
	v_mul_f32_e32 v117, v124, v124
	v_mul_f32_e32 v118, v127, v127
	v_fmac_f32_e32 v117, v125, v125
	v_fmac_f32_e32 v118, v126, v126
	v_add_f32_e32 v117, v118, v117
	v_and_b32_e32 v118, 64, v169
	v_add_f32_e32 v116, v117, v116
	v_xor_b32_e32 v117, 16, v169
	v_add_u32_e32 v118, 64, v118
	v_cmp_lt_i32_e32 vcc, v117, v118
	v_add_f32_e32 v116, v188, v116
	s_nop 0
	v_cndmask_b32_e32 v117, v169, v117, vcc
	v_lshlrev_b32_e32 v128, 2, v117
	ds_bpermute_b32 v117, v128, v116
	s_waitcnt lgkmcnt(0)
	v_add_f32_e32 v116, v116, v117
	v_xor_b32_e32 v117, 32, v169
	v_cmp_lt_i32_e32 vcc, v117, v118
	s_nop 1
	v_cndmask_b32_e32 v117, v169, v117, vcc
	v_lshlrev_b32_e32 v129, 2, v117
	ds_bpermute_b32 v117, v129, v116
	s_and_saveexec_b64 s[18:19], s[2:3]
	s_cbranch_execz .LBB0_488
	s_waitcnt lgkmcnt(0)
	v_add_f32_e32 v116, v116, v117
	v_fma_f32 v116, v116, s60, 0.5
	v_cvt_u32_f32_e32 v118, v116
	v_lshl_add_u64 v[116:117], v[160:161], 2, s[0:1]
	global_atomic_add v[116:117], v118, off
; __device__ __forceinline__ unsigned cvt_pk_bf16(float lo, float hi) { unsigned r; asm volatile("v_cvt_pk_bf16_f32 %0, %1, %2" : "=v"(r) : "v"(lo), "v"(hi)); return r; }
;     __device__ __forceinline__ void operator()(const f32x4 (&acc)[2][2][4][2], const Unit& u, int wr, int wc, int fr, int fq, const float (&)[8]) const {
;     ...
;         for (int g = 0; g < 8; ++g) { const int ai = g >> 2, m = g & 3, row = row0 + ai * HALF + m * 16; const size_t off = (size_t)row * 2048 + col0; float ss = 0.f;
;             if (g + 1 < 8) { const size_t offn = (size_t)(row0 + ((g + 1) >> 2) * HALF + ((g + 1) & 3) * 16) * 2048 + col0;
; #pragma unroll
;                 for (int bj = 0; bj < 2; ++bj) xn[bj] = *(const u32x4*)(xb + offn + bj * HALF); }
; #pragma unroll
;             for (int bj = 0; bj < 2; ++bj) { const size_t o = off + bj * HALF; const u32x4 xw = xc[bj];
;                 const f32x4 x0 = (f32x4){__uint_as_float(xw.x << 16), __uint_as_float(xw.x & 0xffff0000u), __uint_as_float(xw.y << 16), __uint_as_float(xw.y & 0xffff0000u)};
;                 const f32x4 x1 = (f32x4){__uint_as_float(xw.z << 16), __uint_as_float(xw.z & 0xffff0000u), __uint_as_float(xw.w << 16), __uint_as_float(xw.w & 0xffff0000u)};
;                 const f32x4 v0 = x0 + acc[ai][bj][m][0] * alpha, v1 = x1 + acc[ai][bj][m][1] * alpha;
;                 if (xf) { *(f32x4*)(xf + o) = v0; *(f32x4*)(xf + o + 4) = v1; }
;                 else { u32x4 w; w.x = cvt_pk_bf16(v0[0], v0[1]); w.y = cvt_pk_bf16(v0[2], v0[3]); w.z = cvt_pk_bf16(v1[0], v1[1]); w.w = cvt_pk_bf16(v1[2], v1[3]); *(u32x4*)(xb + o) = w; }
;                 ss += ((v0[0] * v0[0] + v0[1] * v0[1]) + (v0[2] * v0[2] + v0[3] * v0[3])) + ((v1[0] * v1[0] + v1[1] * v1[1]) + (v1[2] * v1[2] + v1[3] * v1[3])); }
;             ss += __shfl_xor(ss, 16); ss += __shfl_xor(ss, 32);
;             if (fq == 0) (void)__hip_atomic_fetch_add((unsigned*)(ssq_out + row), (unsigned)(ss * SSQ_SCALE + 0.5f), __ATOMIC_RELAXED, __HIP_MEMORY_SCOPE_AGENT);
.LBB0_488:
	s_or_b64 exec, exec, s[18:19]
	v_or_b32_e32 v124, 32, v160
	v_ashrrev_i32_e32 v125, 31, v124
	s_waitcnt lgkmcnt(0)
	v_lshlrev_b64 v[116:117], 12, v[124:125]
	v_lshl_add_u64 v[116:117], s[46:47], 0, v[116:117]
	v_lshl_add_u64 v[126:127], v[158:159], 1, v[116:117]
	s_waitcnt vmcnt(12)
	v_mov_b32_e32 v120, v200
	v_mov_b32_e32 v121, v201
	v_mov_b32_e32 v122, v202
	v_mov_b32_e32 v123, v203
	v_mov_b32_e32 v116, v204
	v_mov_b32_e32 v117, v205
	v_mov_b32_e32 v118, v206
	v_mov_b32_e32 v119, v207
	v_lshlrev_b32_e32 v130, 16, v136
	v_and_b32_e32 v131, 0xffff0000, v136
	v_lshlrev_b32_e32 v136, 16, v137
	v_and_b32_e32 v137, 0xffff0000, v137
	v_lshlrev_b32_e32 v166, 16, v138
	v_and_b32_e32 v167, 0xffff0000, v138
	v_lshlrev_b32_e32 v138, 16, v139
	v_and_b32_e32 v139, 0xffff0000, v139
	v_pk_add_f32 v[114:115], v[114:115], v[136:137]
	v_pk_add_f32 v[112:113], v[112:113], v[130:131]
	v_pk_add_f32 v[136:137], v[110:111], v[138:139]
	v_mul_f32_e32 v110, v112, v112
	v_mul_f32_e32 v111, v114, v114
	v_pk_add_f32 v[130:131], v[108:109], v[166:167]
	v_fmac_f32_e32 v110, v113, v113
	v_fmac_f32_e32 v111, v115, v115
	v_cvt_pk_bf16_f32 v108, v112, v113
	v_add_f32_e32 v110, v111, v110
	v_mul_f32_e32 v111, v130, v130
	v_mul_f32_e32 v112, v137, v137
	v_fmac_f32_e32 v111, v131, v131
	v_fmac_f32_e32 v112, v136, v136
	v_add_f32_e32 v111, v112, v111
	v_add_f32_e32 v138, v111, v110
	v_lshlrev_b32_e32 v110, 16, v132
	v_and_b32_e32 v111, 0xffff0000, v132
	v_lshlrev_b32_e32 v112, 16, v133
	v_and_b32_e32 v113, 0xffff0000, v133
	v_cvt_pk_bf16_f32 v109, v114, v115
	v_lshlrev_b32_e32 v114, 16, v134
	v_and_b32_e32 v115, 0xffff0000, v134
	v_pk_add_f32 v[106:107], v[106:107], v[112:113]
	v_pk_add_f32 v[104:105], v[104:105], v[110:111]
	v_lshlrev_b32_e32 v132, 16, v135
	v_and_b32_e32 v133, 0xffff0000, v135
	v_pk_add_f32 v[112:113], v[100:101], v[114:115]
	v_mul_f32_e32 v100, v104, v104
	v_mul_f32_e32 v101, v106, v106
	v_pk_add_f32 v[114:115], v[102:103], v[132:133]
	v_fmac_f32_e32 v100, v105, v105
	v_fmac_f32_e32 v101, v107, v107
	v_add_f32_e32 v100, v101, v100
	v_mul_f32_e32 v101, v112, v112
	v_mul_f32_e32 v102, v115, v115
	v_fmac_f32_e32 v101, v113, v113
	v_fmac_f32_e32 v102, v114, v114
	v_add_f32_e32 v101, v102, v101
	v_add_f32_e32 v100, v101, v100
	v_add_f32_e32 v100, v138, v100
	ds_bpermute_b32 v101, v128, v100
	v_cvt_pk_bf16_f32 v110, v130, v131
	v_cvt_pk_bf16_f32 v111, v136, v137
	global_store_dwordx4 v[164:165], v[108:111], off
	v_cvt_pk_bf16_f32 v102, v104, v105
	s_waitcnt lgkmcnt(0)
	v_add_f32_e32 v100, v100, v101
	ds_bpermute_b32 v101, v129, v100
	v_cvt_pk_bf16_f32 v103, v106, v107
	v_cvt_pk_bf16_f32 v104, v112, v113
	v_cvt_pk_bf16_f32 v105, v114, v115
	global_store_dwordx4 v[164:165], v[102:105], off offset:256
	s_and_saveexec_b64 s[18:19], s[2:3]
	s_cbranch_execz .LBB0_490
	s_waitcnt lgkmcnt(0)
	v_add_f32_e32 v100, v100, v101
	v_fma_f32 v100, v100, s60, 0.5
	v_cvt_u32_f32_e32 v102, v100
	v_lshl_add_u64 v[100:101], v[162:163], 2, s[0:1]
	global_atomic_add v[100:101], v102, off
.LBB0_490:
	s_or_b64 exec, exec, s[18:19]
	v_or_b32_e32 v108, 48, v160
	v_ashrrev_i32_e32 v109, 31, v108
	s_waitcnt lgkmcnt(0)
	v_lshlrev_b64 v[100:101], 12, v[108:109]
	v_lshl_add_u64 v[100:101], s[46:47], 0, v[100:101]
	v_lshl_add_u64 v[110:111], v[158:159], 1, v[100:101]
	s_waitcnt vmcnt(12)
	v_mov_b32_e32 v104, v208
	v_mov_b32_e32 v105, v209
	v_mov_b32_e32 v106, v210
	v_mov_b32_e32 v107, v211
	v_mov_b32_e32 v100, v212
	v_mov_b32_e32 v101, v213
	v_mov_b32_e32 v102, v214
	v_mov_b32_e32 v103, v215
	v_lshlrev_b32_e32 v112, 16, v120
	v_and_b32_e32 v113, 0xffff0000, v120
	v_lshlrev_b32_e32 v114, 16, v121
	v_and_b32_e32 v115, 0xffff0000, v121
	v_lshlrev_b32_e32 v120, 16, v122
	v_and_b32_e32 v121, 0xffff0000, v122
	v_lshlrev_b32_e32 v122, 16, v123
	v_and_b32_e32 v123, 0xffff0000, v123
	v_pk_add_f32 v[98:99], v[98:99], v[114:115]
	v_pk_add_f32 v[96:97], v[96:97], v[112:113]
	v_pk_add_f32 v[114:115], v[94:95], v[122:123]
	v_mul_f32_e32 v94, v96, v96
	v_mul_f32_e32 v95, v98, v98
	v_pk_add_f32 v[112:113], v[92:93], v[120:121]
	v_fmac_f32_e32 v94, v97, v97
	v_fmac_f32_e32 v95, v99, v99
	v_cvt_pk_bf16_f32 v92, v96, v97
	v_add_f32_e32 v94, v95, v94
	v_mul_f32_e32 v95, v112, v112
	v_mul_f32_e32 v96, v115, v115
	v_fmac_f32_e32 v95, v113, v113
	v_fmac_f32_e32 v96, v114, v114
	v_add_f32_e32 v95, v96, v95
	v_add_f32_e32 v120, v95, v94
	v_lshlrev_b32_e32 v94, 16, v116
	v_and_b32_e32 v95, 0xffff0000, v116
	v_lshlrev_b32_e32 v96, 16, v117
	v_and_b32_e32 v97, 0xffff0000, v117
	v_cvt_pk_bf16_f32 v93, v98, v99
	v_lshlrev_b32_e32 v98, 16, v118
	v_and_b32_e32 v99, 0xffff0000, v118
	v_pk_add_f32 v[90:91], v[90:91], v[96:97]
	v_pk_add_f32 v[88:89], v[88:89], v[94:95]
	v_lshlrev_b32_e32 v116, 16, v119
	v_and_b32_e32 v117, 0xffff0000, v119
	v_pk_add_f32 v[96:97], v[84:85], v[98:99]
	v_mul_f32_e32 v84, v88, v88
	v_mul_f32_e32 v85, v90, v90
	v_pk_add_f32 v[98:99], v[86:87], v[116:117]
	v_fmac_f32_e32 v84, v89, v89
	v_fmac_f32_e32 v85, v91, v91
	v_add_f32_e32 v84, v85, v84
	v_mul_f32_e32 v85, v96, v96
	v_mul_f32_e32 v86, v99, v99
	v_fmac_f32_e32 v85, v97, v97
	v_fmac_f32_e32 v86, v98, v98
	v_add_f32_e32 v85, v86, v85
	v_add_f32_e32 v84, v85, v84
	v_add_f32_e32 v84, v120, v84
	ds_bpermute_b32 v85, v128, v84
	v_cvt_pk_bf16_f32 v94, v112, v113
	v_cvt_pk_bf16_f32 v95, v114, v115
	global_store_dwordx4 v[126:127], v[92:95], off
	v_cvt_pk_bf16_f32 v86, v88, v89
	s_waitcnt lgkmcnt(0)
	v_add_f32_e32 v84, v84, v85
	ds_bpermute_b32 v85, v129, v84
	v_cvt_pk_bf16_f32 v87, v90, v91
	v_cvt_pk_bf16_f32 v88, v96, v97
	v_cvt_pk_bf16_f32 v89, v98, v99
	global_store_dwordx4 v[126:127], v[86:89], off offset:256
	s_and_saveexec_b64 s[18:19], s[2:3]
	s_cbranch_execz .LBB0_492
	s_waitcnt lgkmcnt(0)
	v_add_f32_e32 v84, v84, v85
	v_fma_f32 v84, v84, s60, 0.5
	v_cvt_u32_f32_e32 v86, v84
	v_lshl_add_u64 v[84:85], v[124:125], 2, s[0:1]
	global_atomic_add v[84:85], v86, off
; __device__ __forceinline__ unsigned cvt_pk_bf16(float lo, float hi) { unsigned r; asm volatile("v_cvt_pk_bf16_f32 %0, %1, %2" : "=v"(r) : "v"(lo), "v"(hi)); return r; }
;     __device__ __forceinline__ void operator()(const f32x4 (&acc)[2][2][4][2], const Unit& u, int wr, int wc, int fr, int fq, const float (&)[8]) const {
;     ...
;         for (int g = 0; g < 8; ++g) { const int ai = g >> 2, m = g & 3, row = row0 + ai * HALF + m * 16; const size_t off = (size_t)row * 2048 + col0; float ss = 0.f;
;             if (g + 1 < 8) { const size_t offn = (size_t)(row0 + ((g + 1) >> 2) * HALF + ((g + 1) & 3) * 16) * 2048 + col0;
; #pragma unroll
;                 for (int bj = 0; bj < 2; ++bj) xn[bj] = *(const u32x4*)(xb + offn + bj * HALF); }
; #pragma unroll
;             for (int bj = 0; bj < 2; ++bj) { const size_t o = off + bj * HALF; const u32x4 xw = xc[bj];
;                 const f32x4 x0 = (f32x4){__uint_as_float(xw.x << 16), __uint_as_float(xw.x & 0xffff0000u), __uint_as_float(xw.y << 16), __uint_as_float(xw.y & 0xffff0000u)};
;                 const f32x4 x1 = (f32x4){__uint_as_float(xw.z << 16), __uint_as_float(xw.z & 0xffff0000u), __uint_as_float(xw.w << 16), __uint_as_float(xw.w & 0xffff0000u)};
;                 const f32x4 v0 = x0 + acc[ai][bj][m][0] * alpha, v1 = x1 + acc[ai][bj][m][1] * alpha;
;                 if (xf) { *(f32x4*)(xf + o) = v0; *(f32x4*)(xf + o + 4) = v1; }
;                 else { u32x4 w; w.x = cvt_pk_bf16(v0[0], v0[1]); w.y = cvt_pk_bf16(v0[2], v0[3]); w.z = cvt_pk_bf16(v1[0], v1[1]); w.w = cvt_pk_bf16(v1[2], v1[3]); *(u32x4*)(xb + o) = w; }
;                 ss += ((v0[0] * v0[0] + v0[1] * v0[1]) + (v0[2] * v0[2] + v0[3] * v0[3])) + ((v1[0] * v1[0] + v1[1] * v1[1]) + (v1[2] * v1[2] + v1[3] * v1[3])); }
;             ss += __shfl_xor(ss, 16); ss += __shfl_xor(ss, 32);
;             if (fq == 0) (void)__hip_atomic_fetch_add((unsigned*)(ssq_out + row), (unsigned)(ss * SSQ_SCALE + 0.5f), __ATOMIC_RELAXED, __HIP_MEMORY_SCOPE_AGENT);
; #pragma unroll
;             for (int bj = 0; bj < 2; ++bj) xc[bj] = xn[bj]; }
.LBB0_492:
	s_or_b64 exec, exec, s[18:19]
	v_add_u32_e32 v92, 0x80, v160
	v_ashrrev_i32_e32 v93, 31, v92
	s_waitcnt lgkmcnt(0)
	v_lshlrev_b64 v[84:85], 12, v[92:93]
	v_lshl_add_u64 v[84:85], s[46:47], 0, v[84:85]
	v_lshl_add_u64 v[94:95], v[158:159], 1, v[84:85]
	s_waitcnt vmcnt(12)
	v_mov_b32_e32 v88, v216
	v_mov_b32_e32 v89, v217
	v_mov_b32_e32 v90, v218
	v_mov_b32_e32 v91, v219
	v_mov_b32_e32 v84, v220
	v_mov_b32_e32 v85, v221
	v_mov_b32_e32 v86, v222
	v_mov_b32_e32 v87, v223
	v_lshlrev_b32_e32 v96, 16, v104
	v_and_b32_e32 v97, 0xffff0000, v104
	v_lshlrev_b32_e32 v98, 16, v105
	v_and_b32_e32 v99, 0xffff0000, v105
	v_lshlrev_b32_e32 v104, 16, v106
	v_and_b32_e32 v105, 0xffff0000, v106
	v_lshlrev_b32_e32 v106, 16, v107
	v_and_b32_e32 v107, 0xffff0000, v107
	v_pk_add_f32 v[82:83], v[82:83], v[98:99]
	v_pk_add_f32 v[80:81], v[80:81], v[96:97]
	v_pk_add_f32 v[98:99], v[78:79], v[106:107]
	v_mul_f32_e32 v78, v80, v80
	v_mul_f32_e32 v79, v82, v82
	v_pk_add_f32 v[96:97], v[76:77], v[104:105]
	v_fmac_f32_e32 v78, v81, v81
	v_fmac_f32_e32 v79, v83, v83
	v_cvt_pk_bf16_f32 v76, v80, v81
	v_add_f32_e32 v78, v79, v78
	v_mul_f32_e32 v79, v96, v96
	v_mul_f32_e32 v80, v99, v99
	v_fmac_f32_e32 v79, v97, v97
	v_fmac_f32_e32 v80, v98, v98
	v_add_f32_e32 v79, v80, v79
	v_add_f32_e32 v104, v79, v78
	v_lshlrev_b32_e32 v78, 16, v100
	v_and_b32_e32 v79, 0xffff0000, v100
	v_lshlrev_b32_e32 v80, 16, v101
	v_and_b32_e32 v81, 0xffff0000, v101
	v_cvt_pk_bf16_f32 v77, v82, v83
	v_lshlrev_b32_e32 v82, 16, v102
	v_and_b32_e32 v83, 0xffff0000, v102
	v_pk_add_f32 v[74:75], v[74:75], v[80:81]
	v_pk_add_f32 v[72:73], v[72:73], v[78:79]
	v_lshlrev_b32_e32 v100, 16, v103
	v_and_b32_e32 v101, 0xffff0000, v103
	v_pk_add_f32 v[80:81], v[68:69], v[82:83]
	v_mul_f32_e32 v68, v72, v72
	v_mul_f32_e32 v69, v74, v74
	v_pk_add_f32 v[82:83], v[70:71], v[100:101]
	v_fmac_f32_e32 v68, v73, v73
	v_fmac_f32_e32 v69, v75, v75
	v_add_f32_e32 v68, v69, v68
	v_mul_f32_e32 v69, v80, v80
	v_mul_f32_e32 v70, v83, v83
	v_fmac_f32_e32 v69, v81, v81
	v_fmac_f32_e32 v70, v82, v82
	v_add_f32_e32 v69, v70, v69
	v_add_f32_e32 v68, v69, v68
	v_add_f32_e32 v68, v104, v68
	ds_bpermute_b32 v69, v128, v68
	v_cvt_pk_bf16_f32 v78, v96, v97
	v_cvt_pk_bf16_f32 v79, v98, v99
	global_store_dwordx4 v[110:111], v[76:79], off
	v_cvt_pk_bf16_f32 v70, v72, v73
	s_waitcnt lgkmcnt(0)
	v_add_f32_e32 v68, v68, v69
	ds_bpermute_b32 v69, v129, v68
	v_cvt_pk_bf16_f32 v71, v74, v75
	v_cvt_pk_bf16_f32 v72, v80, v81
	v_cvt_pk_bf16_f32 v73, v82, v83
	global_store_dwordx4 v[110:111], v[70:73], off offset:256
	s_and_saveexec_b64 s[18:19], s[2:3]
	s_cbranch_execz .LBB0_494
	s_waitcnt lgkmcnt(0)
	v_add_f32_e32 v68, v68, v69
	v_fma_f32 v68, v68, s60, 0.5
	v_cvt_u32_f32_e32 v70, v68
	v_lshl_add_u64 v[68:69], v[108:109], 2, s[0:1]
	global_atomic_add v[68:69], v70, off
.LBB0_494:
	s_or_b64 exec, exec, s[18:19]
	v_or_b32_e32 v76, 16, v92
	v_ashrrev_i32_e32 v77, 31, v76
	s_waitcnt lgkmcnt(0)
	v_lshlrev_b64 v[68:69], 12, v[76:77]
	v_lshl_add_u64 v[68:69], s[46:47], 0, v[68:69]
	v_lshl_add_u64 v[78:79], v[158:159], 1, v[68:69]
	s_waitcnt vmcnt(12)
	v_mov_b32_e32 v72, v224
	v_mov_b32_e32 v73, v225
	v_mov_b32_e32 v74, v226
	v_mov_b32_e32 v75, v227
	v_mov_b32_e32 v68, v228
	v_mov_b32_e32 v69, v229
	v_mov_b32_e32 v70, v230
	v_mov_b32_e32 v71, v231
	v_lshlrev_b32_e32 v80, 16, v88
	v_and_b32_e32 v81, 0xffff0000, v88
	v_lshlrev_b32_e32 v82, 16, v89
	v_and_b32_e32 v83, 0xffff0000, v89
	v_lshlrev_b32_e32 v88, 16, v90
	v_and_b32_e32 v89, 0xffff0000, v90
	v_lshlrev_b32_e32 v90, 16, v91
	v_and_b32_e32 v91, 0xffff0000, v91
	v_pk_add_f32 v[66:67], v[66:67], v[82:83]
	v_pk_add_f32 v[64:65], v[64:65], v[80:81]
	v_pk_add_f32 v[82:83], v[62:63], v[90:91]
	v_mul_f32_e32 v62, v64, v64
	v_mul_f32_e32 v63, v66, v66
	v_pk_add_f32 v[80:81], v[60:61], v[88:89]
	v_fmac_f32_e32 v62, v65, v65
	v_fmac_f32_e32 v63, v67, v67
	v_cvt_pk_bf16_f32 v60, v64, v65
	v_add_f32_e32 v62, v63, v62
	v_mul_f32_e32 v63, v80, v80
	v_mul_f32_e32 v64, v83, v83
	v_fmac_f32_e32 v63, v81, v81
	v_fmac_f32_e32 v64, v82, v82
	v_add_f32_e32 v63, v64, v63
	v_add_f32_e32 v88, v63, v62
	v_lshlrev_b32_e32 v62, 16, v84
	v_and_b32_e32 v63, 0xffff0000, v84
	v_lshlrev_b32_e32 v64, 16, v85
	v_and_b32_e32 v65, 0xffff0000, v85
	v_cvt_pk_bf16_f32 v61, v66, v67
	v_lshlrev_b32_e32 v66, 16, v86
	v_and_b32_e32 v67, 0xffff0000, v86
	v_pk_add_f32 v[58:59], v[58:59], v[64:65]
	v_pk_add_f32 v[56:57], v[56:57], v[62:63]
	v_lshlrev_b32_e32 v84, 16, v87
	v_and_b32_e32 v85, 0xffff0000, v87
	v_pk_add_f32 v[64:65], v[52:53], v[66:67]
	v_mul_f32_e32 v52, v56, v56
	v_mul_f32_e32 v53, v58, v58
	v_pk_add_f32 v[66:67], v[54:55], v[84:85]
	v_fmac_f32_e32 v52, v57, v57
	v_fmac_f32_e32 v53, v59, v59
	v_add_f32_e32 v52, v53, v52
	v_mul_f32_e32 v53, v64, v64
	v_mul_f32_e32 v54, v67, v67
	v_fmac_f32_e32 v53, v65, v65
	v_fmac_f32_e32 v54, v66, v66
	v_add_f32_e32 v53, v54, v53
	v_add_f32_e32 v52, v53, v52
	v_add_f32_e32 v52, v88, v52
	ds_bpermute_b32 v53, v128, v52
	v_cvt_pk_bf16_f32 v62, v80, v81
	v_cvt_pk_bf16_f32 v63, v82, v83
	global_store_dwordx4 v[94:95], v[60:63], off
	v_cvt_pk_bf16_f32 v54, v56, v57
	s_waitcnt lgkmcnt(0)
	v_add_f32_e32 v52, v52, v53
	ds_bpermute_b32 v53, v129, v52
	v_cvt_pk_bf16_f32 v55, v58, v59
	v_cvt_pk_bf16_f32 v56, v64, v65
	v_cvt_pk_bf16_f32 v57, v66, v67
	global_store_dwordx4 v[94:95], v[54:57], off offset:256
	s_and_saveexec_b64 s[18:19], s[2:3]
	s_cbranch_execz .LBB0_496
	s_waitcnt lgkmcnt(0)
	v_add_f32_e32 v52, v52, v53
	v_fma_f32 v52, v52, s60, 0.5
	v_cvt_u32_f32_e32 v54, v52
	v_lshl_add_u64 v[52:53], v[92:93], 2, s[0:1]
	global_atomic_add v[52:53], v54, off
; __device__ __forceinline__ unsigned cvt_pk_bf16(float lo, float hi) { unsigned r; asm volatile("v_cvt_pk_bf16_f32 %0, %1, %2" : "=v"(r) : "v"(lo), "v"(hi)); return r; }
;     __device__ __forceinline__ void operator()(const f32x4 (&acc)[2][2][4][2], const Unit& u, int wr, int wc, int fr, int fq, const float (&)[8]) const {
;     ...
;         for (int g = 0; g < 8; ++g) { const int ai = g >> 2, m = g & 3, row = row0 + ai * HALF + m * 16; const size_t off = (size_t)row * 2048 + col0; float ss = 0.f;
;             if (g + 1 < 8) { const size_t offn = (size_t)(row0 + ((g + 1) >> 2) * HALF + ((g + 1) & 3) * 16) * 2048 + col0;
; #pragma unroll
;                 for (int bj = 0; bj < 2; ++bj) xn[bj] = *(const u32x4*)(xb + offn + bj * HALF); }
; #pragma unroll
;             for (int bj = 0; bj < 2; ++bj) { const size_t o = off + bj * HALF; const u32x4 xw = xc[bj];
;                 const f32x4 x0 = (f32x4){__uint_as_float(xw.x << 16), __uint_as_float(xw.x & 0xffff0000u), __uint_as_float(xw.y << 16), __uint_as_float(xw.y & 0xffff0000u)};
;                 const f32x4 x1 = (f32x4){__uint_as_float(xw.z << 16), __uint_as_float(xw.z & 0xffff0000u), __uint_as_float(xw.w << 16), __uint_as_float(xw.w & 0xffff0000u)};
;                 const f32x4 v0 = x0 + acc[ai][bj][m][0] * alpha, v1 = x1 + acc[ai][bj][m][1] * alpha;
;                 if (xf) { *(f32x4*)(xf + o) = v0; *(f32x4*)(xf + o + 4) = v1; }
;                 else { u32x4 w; w.x = cvt_pk_bf16(v0[0], v0[1]); w.y = cvt_pk_bf16(v0[2], v0[3]); w.z = cvt_pk_bf16(v1[0], v1[1]); w.w = cvt_pk_bf16(v1[2], v1[3]); *(u32x4*)(xb + o) = w; }
;                 ss += ((v0[0] * v0[0] + v0[1] * v0[1]) + (v0[2] * v0[2] + v0[3] * v0[3])) + ((v1[0] * v1[0] + v1[1] * v1[1]) + (v1[2] * v1[2] + v1[3] * v1[3])); }
;             ss += __shfl_xor(ss, 16); ss += __shfl_xor(ss, 32);
;             if (fq == 0) (void)__hip_atomic_fetch_add((unsigned*)(ssq_out + row), (unsigned)(ss * SSQ_SCALE + 0.5f), __ATOMIC_RELAXED, __HIP_MEMORY_SCOPE_AGENT);
; #pragma unroll
;             for (int bj = 0; bj < 2; ++bj) xc[bj] = xn[bj]; }
.LBB0_496:
	s_or_b64 exec, exec, s[18:19]
	v_or_b32_e32 v60, 32, v92
	v_ashrrev_i32_e32 v61, 31, v60
	s_waitcnt lgkmcnt(0)
	v_lshlrev_b64 v[52:53], 12, v[60:61]
	v_lshl_add_u64 v[52:53], s[46:47], 0, v[52:53]
	v_lshl_add_u64 v[62:63], v[158:159], 1, v[52:53]
	s_waitcnt vmcnt(12)
	v_mov_b32_e32 v56, v232
	v_mov_b32_e32 v57, v233
	v_mov_b32_e32 v58, v234
	v_mov_b32_e32 v59, v235
	v_mov_b32_e32 v52, v236
	v_mov_b32_e32 v53, v237
	v_mov_b32_e32 v54, v238
	v_mov_b32_e32 v55, v239
	v_lshlrev_b32_e32 v64, 16, v72
	v_and_b32_e32 v65, 0xffff0000, v72
	v_lshlrev_b32_e32 v66, 16, v73
	v_and_b32_e32 v67, 0xffff0000, v73
	v_lshlrev_b32_e32 v72, 16, v74
	v_and_b32_e32 v73, 0xffff0000, v74
	v_lshlrev_b32_e32 v74, 16, v75
	v_and_b32_e32 v75, 0xffff0000, v75
	v_pk_add_f32 v[50:51], v[50:51], v[66:67]
	v_pk_add_f32 v[48:49], v[48:49], v[64:65]
	v_pk_add_f32 v[66:67], v[46:47], v[74:75]
	v_mul_f32_e32 v46, v48, v48
	v_mul_f32_e32 v47, v50, v50
	v_pk_add_f32 v[64:65], v[44:45], v[72:73]
	v_fmac_f32_e32 v46, v49, v49
	v_fmac_f32_e32 v47, v51, v51
	v_cvt_pk_bf16_f32 v44, v48, v49
	v_add_f32_e32 v46, v47, v46
	v_mul_f32_e32 v47, v64, v64
	v_mul_f32_e32 v48, v67, v67
	v_fmac_f32_e32 v47, v65, v65
	v_fmac_f32_e32 v48, v66, v66
	v_add_f32_e32 v47, v48, v47
	v_add_f32_e32 v72, v47, v46
	v_lshlrev_b32_e32 v46, 16, v68
	v_and_b32_e32 v47, 0xffff0000, v68
	v_lshlrev_b32_e32 v48, 16, v69
	v_and_b32_e32 v49, 0xffff0000, v69
	v_cvt_pk_bf16_f32 v45, v50, v51
	v_lshlrev_b32_e32 v50, 16, v70
	v_and_b32_e32 v51, 0xffff0000, v70
	v_pk_add_f32 v[42:43], v[42:43], v[48:49]
	v_pk_add_f32 v[40:41], v[40:41], v[46:47]
	v_lshlrev_b32_e32 v68, 16, v71
	v_and_b32_e32 v69, 0xffff0000, v71
	v_pk_add_f32 v[48:49], v[36:37], v[50:51]
	v_mul_f32_e32 v36, v40, v40
	v_mul_f32_e32 v37, v42, v42
	v_pk_add_f32 v[50:51], v[38:39], v[68:69]
	v_fmac_f32_e32 v36, v41, v41
	v_fmac_f32_e32 v37, v43, v43
	v_add_f32_e32 v36, v37, v36
	v_mul_f32_e32 v37, v48, v48
	v_mul_f32_e32 v38, v51, v51
	v_fmac_f32_e32 v37, v49, v49
	v_fmac_f32_e32 v38, v50, v50
	v_add_f32_e32 v37, v38, v37
	v_add_f32_e32 v36, v37, v36
	v_add_f32_e32 v36, v72, v36
	ds_bpermute_b32 v37, v128, v36
	v_cvt_pk_bf16_f32 v46, v64, v65
	v_cvt_pk_bf16_f32 v47, v66, v67
	global_store_dwordx4 v[78:79], v[44:47], off
	v_cvt_pk_bf16_f32 v38, v40, v41
	s_waitcnt lgkmcnt(0)
	v_add_f32_e32 v36, v36, v37
	ds_bpermute_b32 v37, v129, v36
	v_cvt_pk_bf16_f32 v39, v42, v43
	v_cvt_pk_bf16_f32 v40, v48, v49
	v_cvt_pk_bf16_f32 v41, v50, v51
	global_store_dwordx4 v[78:79], v[38:41], off offset:256
	s_and_saveexec_b64 s[18:19], s[2:3]
	s_cbranch_execz .LBB0_498
	s_waitcnt lgkmcnt(0)
	v_add_f32_e32 v36, v36, v37
	v_fma_f32 v36, v36, s60, 0.5
	v_cvt_u32_f32_e32 v38, v36
	v_lshl_add_u64 v[36:37], v[76:77], 2, s[0:1]
	global_atomic_add v[36:37], v38, off
; __device__ __forceinline__ unsigned cvt_pk_bf16(float lo, float hi) { unsigned r; asm volatile("v_cvt_pk_bf16_f32 %0, %1, %2" : "=v"(r) : "v"(lo), "v"(hi)); return r; }
;     __device__ __forceinline__ void operator()(const f32x4 (&acc)[2][2][4][2], const Unit& u, int wr, int wc, int fr, int fq, const float (&)[8]) const {
;     ...
;         for (int g = 0; g < 8; ++g) { const int ai = g >> 2, m = g & 3, row = row0 + ai * HALF + m * 16; const size_t off = (size_t)row * 2048 + col0; float ss = 0.f;
;             if (g + 1 < 8) { const size_t offn = (size_t)(row0 + ((g + 1) >> 2) * HALF + ((g + 1) & 3) * 16) * 2048 + col0;
; #pragma unroll
;                 for (int bj = 0; bj < 2; ++bj) xn[bj] = *(const u32x4*)(xb + offn + bj * HALF); }
; #pragma unroll
;             for (int bj = 0; bj < 2; ++bj) { const size_t o = off + bj * HALF; const u32x4 xw = xc[bj];
;                 const f32x4 x0 = (f32x4){__uint_as_float(xw.x << 16), __uint_as_float(xw.x & 0xffff0000u), __uint_as_float(xw.y << 16), __uint_as_float(xw.y & 0xffff0000u)};
;                 const f32x4 x1 = (f32x4){__uint_as_float(xw.z << 16), __uint_as_float(xw.z & 0xffff0000u), __uint_as_float(xw.w << 16), __uint_as_float(xw.w & 0xffff0000u)};
;                 const f32x4 v0 = x0 + acc[ai][bj][m][0] * alpha, v1 = x1 + acc[ai][bj][m][1] * alpha;
;                 if (xf) { *(f32x4*)(xf + o) = v0; *(f32x4*)(xf + o + 4) = v1; }
;                 else { u32x4 w; w.x = cvt_pk_bf16(v0[0], v0[1]); w.y = cvt_pk_bf16(v0[2], v0[3]); w.z = cvt_pk_bf16(v1[0], v1[1]); w.w = cvt_pk_bf16(v1[2], v1[3]); *(u32x4*)(xb + o) = w; }
;                 ss += ((v0[0] * v0[0] + v0[1] * v0[1]) + (v0[2] * v0[2] + v0[3] * v0[3])) + ((v1[0] * v1[0] + v1[1] * v1[1]) + (v1[2] * v1[2] + v1[3] * v1[3])); }
;             ss += __shfl_xor(ss, 16); ss += __shfl_xor(ss, 32);
;             if (fq == 0) (void)__hip_atomic_fetch_add((unsigned*)(ssq_out + row), (unsigned)(ss * SSQ_SCALE + 0.5f), __ATOMIC_RELAXED, __HIP_MEMORY_SCOPE_AGENT);
; #pragma unroll
;             for (int bj = 0; bj < 2; ++bj) xc[bj] = xn[bj]; }
.LBB0_498:
	s_or_b64 exec, exec, s[18:19]
	v_or_b32_e32 v44, 48, v92
	v_ashrrev_i32_e32 v45, 31, v44
	s_waitcnt lgkmcnt(0)
	v_lshlrev_b64 v[36:37], 12, v[44:45]
	v_lshl_add_u64 v[36:37], s[46:47], 0, v[36:37]
	v_lshl_add_u64 v[46:47], v[158:159], 1, v[36:37]
	s_waitcnt vmcnt(12)
	v_mov_b32_e32 v40, v240
	v_mov_b32_e32 v41, v241
	v_mov_b32_e32 v42, v242
	v_mov_b32_e32 v43, v243
	v_mov_b32_e32 v36, v244
	v_mov_b32_e32 v37, v245
	v_mov_b32_e32 v38, v246
	v_mov_b32_e32 v39, v247
	v_lshlrev_b32_e32 v48, 16, v56
	v_and_b32_e32 v49, 0xffff0000, v56
	v_lshlrev_b32_e32 v50, 16, v57
	v_and_b32_e32 v51, 0xffff0000, v57
	v_lshlrev_b32_e32 v56, 16, v58
	v_and_b32_e32 v57, 0xffff0000, v58
	v_lshlrev_b32_e32 v58, 16, v59
	v_and_b32_e32 v59, 0xffff0000, v59
	v_pk_add_f32 v[34:35], v[34:35], v[50:51]
	v_pk_add_f32 v[32:33], v[32:33], v[48:49]
	v_pk_add_f32 v[50:51], v[30:31], v[58:59]
	v_mul_f32_e32 v30, v32, v32
	v_mul_f32_e32 v31, v34, v34
	v_pk_add_f32 v[48:49], v[28:29], v[56:57]
	v_fmac_f32_e32 v30, v33, v33
	v_fmac_f32_e32 v31, v35, v35
	v_cvt_pk_bf16_f32 v28, v32, v33
	v_add_f32_e32 v30, v31, v30
	v_mul_f32_e32 v31, v48, v48
	v_mul_f32_e32 v32, v51, v51
	v_fmac_f32_e32 v31, v49, v49
	v_fmac_f32_e32 v32, v50, v50
	v_add_f32_e32 v31, v32, v31
	v_add_f32_e32 v56, v31, v30
	v_lshlrev_b32_e32 v30, 16, v52
	v_and_b32_e32 v31, 0xffff0000, v52
	v_lshlrev_b32_e32 v32, 16, v53
	v_and_b32_e32 v33, 0xffff0000, v53
	v_cvt_pk_bf16_f32 v29, v34, v35
	v_lshlrev_b32_e32 v34, 16, v54
	v_and_b32_e32 v35, 0xffff0000, v54
	v_pk_add_f32 v[26:27], v[26:27], v[32:33]
	v_pk_add_f32 v[24:25], v[24:25], v[30:31]
	v_lshlrev_b32_e32 v52, 16, v55
	v_and_b32_e32 v53, 0xffff0000, v55
	v_pk_add_f32 v[32:33], v[20:21], v[34:35]
	v_mul_f32_e32 v20, v24, v24
	v_mul_f32_e32 v21, v26, v26
	v_pk_add_f32 v[34:35], v[22:23], v[52:53]
	v_fmac_f32_e32 v20, v25, v25
	v_fmac_f32_e32 v21, v27, v27
	v_add_f32_e32 v20, v21, v20
	v_mul_f32_e32 v21, v32, v32
	v_mul_f32_e32 v22, v35, v35
	v_fmac_f32_e32 v21, v33, v33
	v_fmac_f32_e32 v22, v34, v34
	v_add_f32_e32 v21, v22, v21
	v_add_f32_e32 v20, v21, v20
	v_add_f32_e32 v20, v56, v20
	ds_bpermute_b32 v21, v128, v20
	v_cvt_pk_bf16_f32 v30, v48, v49
	v_cvt_pk_bf16_f32 v31, v50, v51
	global_store_dwordx4 v[62:63], v[28:31], off
	v_cvt_pk_bf16_f32 v22, v24, v25
	s_waitcnt lgkmcnt(0)
	v_add_f32_e32 v20, v20, v21
	ds_bpermute_b32 v21, v129, v20
	v_cvt_pk_bf16_f32 v23, v26, v27
	v_cvt_pk_bf16_f32 v24, v32, v33
	v_cvt_pk_bf16_f32 v25, v34, v35
	global_store_dwordx4 v[62:63], v[22:25], off offset:256
	s_and_saveexec_b64 s[18:19], s[2:3]
	s_cbranch_execz .LBB0_500
	s_waitcnt lgkmcnt(0)
	v_add_f32_e32 v20, v20, v21
	v_fma_f32 v20, v20, s60, 0.5
	v_cvt_u32_f32_e32 v22, v20
	v_lshl_add_u64 v[20:21], v[60:61], 2, s[0:1]
	global_atomic_add v[20:21], v22, off
.LBB0_500:
	s_or_b64 exec, exec, s[18:19]
	v_lshlrev_b32_e32 v20, 16, v40
	s_waitcnt lgkmcnt(0)
	v_and_b32_e32 v21, 0xffff0000, v40
	v_lshlrev_b32_e32 v22, 16, v41
	v_and_b32_e32 v23, 0xffff0000, v41
	v_lshlrev_b32_e32 v26, 16, v43
	v_and_b32_e32 v27, 0xffff0000, v43
	v_pk_add_f32 v[18:19], v[18:19], v[22:23]
	v_pk_add_f32 v[16:17], v[16:17], v[20:21]
	v_lshlrev_b32_e32 v24, 16, v42
	v_and_b32_e32 v25, 0xffff0000, v42
	v_pk_add_f32 v[22:23], v[14:15], v[26:27]
	v_mul_f32_e32 v14, v16, v16
	v_mul_f32_e32 v15, v18, v18
	v_pk_add_f32 v[20:21], v[12:13], v[24:25]
	v_fmac_f32_e32 v14, v17, v17
	v_fmac_f32_e32 v15, v19, v19
	v_cvt_pk_bf16_f32 v12, v16, v17
	v_add_f32_e32 v14, v15, v14
	v_mul_f32_e32 v15, v20, v20
	v_mul_f32_e32 v16, v23, v23
	v_fmac_f32_e32 v15, v21, v21
	v_fmac_f32_e32 v16, v22, v22
	v_add_f32_e32 v15, v16, v15
	v_add_f32_e32 v26, v15, v14
	v_lshlrev_b32_e32 v14, 16, v36
	v_and_b32_e32 v15, 0xffff0000, v36
	v_lshlrev_b32_e32 v16, 16, v37
	v_and_b32_e32 v17, 0xffff0000, v37
	v_cvt_pk_bf16_f32 v13, v18, v19
	v_lshlrev_b32_e32 v18, 16, v38
	v_and_b32_e32 v19, 0xffff0000, v38
	v_pk_add_f32 v[10:11], v[10:11], v[16:17]
	v_pk_add_f32 v[8:9], v[8:9], v[14:15]
	v_lshlrev_b32_e32 v24, 16, v39
	v_and_b32_e32 v25, 0xffff0000, v39
	v_pk_add_f32 v[16:17], v[4:5], v[18:19]
	v_mul_f32_e32 v4, v8, v8
	v_mul_f32_e32 v5, v10, v10
	v_pk_add_f32 v[18:19], v[6:7], v[24:25]
	v_fmac_f32_e32 v4, v9, v9
	v_fmac_f32_e32 v5, v11, v11
	v_add_f32_e32 v4, v5, v4
	v_mul_f32_e32 v5, v16, v16
	v_mul_f32_e32 v6, v19, v19
	v_fmac_f32_e32 v5, v17, v17
	v_fmac_f32_e32 v6, v18, v18
	v_add_f32_e32 v5, v6, v5
	v_add_f32_e32 v4, v5, v4
	v_add_f32_e32 v4, v26, v4
	ds_bpermute_b32 v5, v128, v4
	v_cvt_pk_bf16_f32 v14, v20, v21
	v_cvt_pk_bf16_f32 v15, v22, v23
	global_store_dwordx4 v[46:47], v[12:15], off
	v_cvt_pk_bf16_f32 v6, v8, v9
	s_waitcnt lgkmcnt(0)
	v_add_f32_e32 v4, v4, v5
	ds_bpermute_b32 v5, v129, v4
	v_cvt_pk_bf16_f32 v7, v10, v11
	v_cvt_pk_bf16_f32 v8, v16, v17
	v_cvt_pk_bf16_f32 v9, v18, v19
	global_store_dwordx4 v[46:47], v[6:9], off offset:256
	s_and_saveexec_b64 s[18:19], s[2:3]
	s_cbranch_execz .LBB0_502
	s_waitcnt lgkmcnt(0)
	v_add_f32_e32 v4, v4, v5
	v_fma_f32 v4, v4, s60, 0.5
	v_cvt_u32_f32_e32 v4, v4
	v_lshl_add_u64 v[6:7], v[44:45], 2, s[0:1]
	global_atomic_add v[6:7], v4, off
